# attention epilogue gate (z) loads marked nt as well
# speedup vs baseline: 1.0191x; 1.0038x over previous
; #define SBAR() __builtin_amdgcn_sched_barrier(0)
; __device__ __forceinline__ int crow(int r, int hi) { return (r & 3) + 8 * (r >> 2) + 4 * hi; }
; __device__ __forceinline__ void mla_unit(char* lds, const bf16_t* __restrict__ Qp, const bf16_t* __restrict__ Knp, const bf16_t* __restrict__ Vp, ...
;     ...
;   if (hi == 0) li_l[r32] = l_reg; asm volatile("s_waitcnt lgkmcnt(0)" ::: "memory");
;   float rli[16];
; #pragma unroll
;   for (int r = 0; r < 16; ++r) rli[r] = __builtin_amdgcn_rcpf(li_l[crow(r, hi)]);
;   { unsigned zr[16][4];
; #pragma unroll
;     for (int r = 0; r < 16; ++r) { const long trow = wid * QBLK + crow(r, hi);
; #pragma unroll
;       for (int d0 = 0; d0 < 4; ++d0) zr[r][d0] = Zp[trow * LDZ + d0 * 32 + r32]; }
;     asm volatile("s_waitcnt vmcnt(0)" ::: "memory"); SBAR();
.LBB0_235:
	s_or_b64 exec, exec, s[6:7]
	s_waitcnt lgkmcnt(0)
	ds_read_b128 v[66:69], v90
	ds_read_b128 v[70:73], v90 offset:32
	s_lshl_b32 s0, s38, 22
	s_and_b32 s0, s0, 0x3800000
	s_add_u32 s5, s90, s0
	s_waitcnt lgkmcnt(1)
	v_rcp_f32_e32 v171, v66
	v_rcp_f32_e32 v166, v67
	v_rcp_f32_e32 v161, v68
	v_rcp_f32_e32 v155, v69
	ds_read_b128 v[66:69], v90 offset:64
	s_addc_u32 s6, s91, 0
	s_lshl_b64 s[0:1], s[64:65], 9
	s_add_u32 s0, s5, s0
	s_addc_u32 s1, s6, s1
	s_lshl_b32 s5, s69, 8
	s_and_b32 s5, s5, 0x100
	s_add_u32 s6, s0, s5
	s_waitcnt lgkmcnt(0)
	v_rcp_f32_e32 v128, v66
	v_rcp_f32_e32 v122, v67
	v_rcp_f32_e32 v117, v68
	v_rcp_f32_e32 v111, v69
	ds_read_b128 v[66:69], v90 offset:96
	s_addc_u32 s7, s1, 0
	s_lshl_b32 s0, s38, 15
	s_add_u32 s0, s64, s0
	s_addc_u32 s1, s65, 0
	s_lshl_b64 s[0:1], s[0:1], 7
	s_add_u32 s40, s28, s0
	s_waitcnt lgkmcnt(0)
	v_rcp_f32_e32 v105, v66
	v_rcp_f32_e32 v103, v67
	v_or_b32_e32 v98, s39, v195
	v_lshlrev_b32_e32 v66, 1, v196
	v_mov_b32_e32 v67, v0
	s_addc_u32 s41, s29, s1
	v_rcp_f32_e32 v102, v68
	v_rcp_f32_e32 v1, v69
	v_lshl_add_u64 v[68:69], s[6:7], 0, v[66:67]
	s_mov_b64 s[0:1], 0x2000000
	v_ashrrev_i32_e32 v99, 31, v98
	v_lshl_add_u64 v[100:101], v[68:69], 0, s[0:1]
	v_lshlrev_b64 v[68:69], 9, v[98:99]
	v_or_b32_e32 v96, 1, v98
	v_lshl_add_u64 v[68:69], v[100:101], 0, v[68:69]
	v_ashrrev_i32_e32 v97, 31, v96
	global_load_ushort v180, v[68:69], off nt
	global_load_ushort v177, v[68:69], off offset:64 nt
	global_load_ushort v176, v[68:69], off offset:128 nt
	global_load_ushort v175, v[68:69], off offset:192 nt
	v_lshlrev_b64 v[68:69], 9, v[96:97]
	v_or_b32_e32 v94, 2, v98
	v_lshl_add_u64 v[68:69], v[100:101], 0, v[68:69]
	v_ashrrev_i32_e32 v95, 31, v94
	global_load_ushort v174, v[68:69], off nt
	global_load_ushort v173, v[68:69], off offset:64 nt
	global_load_ushort v172, v[68:69], off offset:128 nt
	global_load_ushort v170, v[68:69], off offset:192 nt
	v_lshlrev_b64 v[68:69], 9, v[94:95]
	v_or_b32_e32 v92, 3, v98
	v_lshl_add_u64 v[68:69], v[100:101], 0, v[68:69]
	v_ashrrev_i32_e32 v93, 31, v92
	global_load_ushort v169, v[68:69], off nt
	global_load_ushort v168, v[68:69], off offset:64 nt
	global_load_ushort v167, v[68:69], off offset:128 nt
	global_load_ushort v165, v[68:69], off offset:192 nt
	v_lshlrev_b64 v[68:69], 9, v[92:93]
	v_or_b32_e32 v90, 8, v98
	v_lshl_add_u64 v[68:69], v[100:101], 0, v[68:69]
	v_ashrrev_i32_e32 v91, 31, v90
	global_load_ushort v164, v[68:69], off nt
	global_load_ushort v163, v[68:69], off offset:64 nt
	global_load_ushort v162, v[68:69], off offset:128 nt
	global_load_ushort v160, v[68:69], off offset:192 nt
	v_lshlrev_b64 v[68:69], 9, v[90:91]
	v_or_b32_e32 v88, 9, v98
	v_lshl_add_u64 v[68:69], v[100:101], 0, v[68:69]
	v_ashrrev_i32_e32 v89, 31, v88
	global_load_ushort v159, v[68:69], off nt
	global_load_ushort v158, v[68:69], off offset:64 nt
	global_load_ushort v157, v[68:69], off offset:128 nt
	global_load_ushort v156, v[68:69], off offset:192 nt
	v_lshlrev_b64 v[68:69], 9, v[88:89]
	v_or_b32_e32 v86, 10, v98
	v_lshl_add_u64 v[68:69], v[100:101], 0, v[68:69]
	v_ashrrev_i32_e32 v87, 31, v86
	global_load_ushort v154, v[68:69], off nt
	global_load_ushort v153, v[68:69], off offset:64 nt
	global_load_ushort v152, v[68:69], off offset:128 nt
	global_load_ushort v151, v[68:69], off offset:192 nt
	v_lshlrev_b64 v[68:69], 9, v[86:87]
	v_or_b32_e32 v84, 11, v98
	v_lshl_add_u64 v[68:69], v[100:101], 0, v[68:69]
	v_ashrrev_i32_e32 v85, 31, v84
	global_load_ushort v149, v[68:69], off nt
	global_load_ushort v148, v[68:69], off offset:64 nt
	global_load_ushort v147, v[68:69], off offset:128 nt
	global_load_ushort v146, v[68:69], off offset:192 nt
	v_lshlrev_b64 v[68:69], 9, v[84:85]
	v_or_b32_e32 v82, 16, v98
	v_lshl_add_u64 v[68:69], v[100:101], 0, v[68:69]
	v_ashrrev_i32_e32 v83, 31, v82
	global_load_ushort v145, v[68:69], off nt
	global_load_ushort v143, v[68:69], off offset:64 nt
	global_load_ushort v142, v[68:69], off offset:128 nt
	global_load_ushort v141, v[68:69], off offset:192 nt
	v_lshlrev_b64 v[68:69], 9, v[82:83]
	v_or_b32_e32 v80, 17, v98
	v_lshl_add_u64 v[68:69], v[100:101], 0, v[68:69]
	v_ashrrev_i32_e32 v81, 31, v80
	global_load_ushort v140, v[68:69], off nt
	global_load_ushort v138, v[68:69], off offset:64 nt
	global_load_ushort v137, v[68:69], off offset:128 nt
	global_load_ushort v136, v[68:69], off offset:192 nt
	v_lshlrev_b64 v[68:69], 9, v[80:81]
	v_or_b32_e32 v78, 18, v98
	v_lshl_add_u64 v[68:69], v[100:101], 0, v[68:69]
	v_ashrrev_i32_e32 v79, 31, v78
	global_load_ushort v135, v[68:69], off nt
	global_load_ushort v134, v[68:69], off offset:64 nt
	global_load_ushort v132, v[68:69], off offset:128 nt
	global_load_ushort v131, v[68:69], off offset:192 nt
	v_lshlrev_b64 v[68:69], 9, v[78:79]
	v_or_b32_e32 v76, 19, v98
	v_lshl_add_u64 v[68:69], v[100:101], 0, v[68:69]
	v_ashrrev_i32_e32 v77, 31, v76
	global_load_ushort v130, v[68:69], off nt
	global_load_ushort v129, v[68:69], off offset:64 nt
	global_load_ushort v127, v[68:69], off offset:128 nt
	global_load_ushort v126, v[68:69], off offset:192 nt
	v_lshlrev_b64 v[68:69], 9, v[76:77]
	v_or_b32_e32 v74, 24, v98
	v_lshl_add_u64 v[68:69], v[100:101], 0, v[68:69]
	v_ashrrev_i32_e32 v75, 31, v74
	v_rcp_f32_e32 v139, v72
	global_load_ushort v125, v[68:69], off nt
	global_load_ushort v124, v[68:69], off offset:64 nt
	global_load_ushort v123, v[68:69], off offset:128 nt
	global_load_ushort v121, v[68:69], off offset:192 nt
	v_lshlrev_b64 v[68:69], 9, v[74:75]
	v_or_b32_e32 v72, 25, v98
	v_rcp_f32_e32 v133, v73
	v_lshl_add_u64 v[68:69], v[100:101], 0, v[68:69]
	v_ashrrev_i32_e32 v73, 31, v72
	v_rcp_f32_e32 v150, v70
	global_load_ushort v120, v[68:69], off nt
	global_load_ushort v119, v[68:69], off offset:64 nt
	global_load_ushort v118, v[68:69], off offset:128 nt
	global_load_ushort v116, v[68:69], off offset:192 nt
	v_lshlrev_b64 v[68:69], 9, v[72:73]
	v_or_b32_e32 v70, 26, v98
	v_rcp_f32_e32 v144, v71
	v_lshl_add_u64 v[68:69], v[100:101], 0, v[68:69]
	v_ashrrev_i32_e32 v71, 31, v70
	global_load_ushort v115, v[68:69], off nt
	global_load_ushort v114, v[68:69], off offset:64 nt
	global_load_ushort v113, v[68:69], off offset:128 nt
	global_load_ushort v112, v[68:69], off offset:192 nt
	v_lshlrev_b64 v[68:69], 9, v[70:71]
	v_lshl_add_u64 v[68:69], v[100:101], 0, v[68:69]
	global_load_ushort v110, v[68:69], off nt
	global_load_ushort v109, v[68:69], off offset:64 nt
	global_load_ushort v108, v[68:69], off offset:128 nt
	global_load_ushort v107, v[68:69], off offset:192 nt
	v_or_b32_e32 v68, 27, v98
	v_ashrrev_i32_e32 v69, 31, v68
	v_lshlrev_b64 v[178:179], 9, v[68:69]
	v_lshl_add_u64 v[178:179], v[100:101], 0, v[178:179]
	global_load_ushort v106, v[178:179], off nt
	global_load_ushort v104, v[178:179], off offset:64 nt
	global_load_ushort v101, v[178:179], off offset:128 nt
	global_load_ushort v100, v[178:179], off offset:192 nt
	s_waitcnt vmcnt(0)
; __device__ __forceinline__ float bf2f(unsigned h) { return __uint_as_float(h << 16); }
; __device__ __forceinline__ unsigned f2bf(float f) { unsigned u = __float_as_uint(f); return (u + 0x7fffu + ((u >> 16) & 1u)) >> 16; }
; __device__ __forceinline__ int crow(int r, int hi) { return (r & 3) + 8 * (r >> 2) + 4 * hi; }
; __device__ __forceinline__ void mla_unit(char* lds, const bf16_t* __restrict__ Qp, const bf16_t* __restrict__ Knp, const bf16_t* __restrict__ Vp, ...
;     ...
; #pragma unroll
;     for (int r = 0; r < 16; ++r) { const long trow = wid * QBLK + crow(r, hi);
; #pragma unroll
;       for (int d0 = 0; d0 < 4; ++d0) { const float z = bf2f(zr[r][d0]); const float v = o[d0][r] * rli[r];
;         const float g = v * z * __builtin_amdgcn_rcpf(1.f + __expf(-z));
;         Op[((size_t)(d0 >> 1) * M_TOK + trow) * 64 + (d0 & 1) * 32 + r32] = (bf16_t)f2bf(g); } } }
	s_waitcnt vmcnt(62)
	v_lshlrev_b32_e32 v178, 16, v180
	v_mul_f32_e32 v50, v50, v171
	v_mul_f32_e32 v50, v50, v178
	v_mul_f32_e32 v178, 0xbfb8aa3b, v178
	v_exp_f32_e32 v178, v178
	v_lshlrev_b64 v[98:99], 7, v[98:99]
	v_lshl_add_u64 v[98:99], s[40:41], 0, v[98:99]
	v_lshl_add_u64 v[98:99], v[98:99], 0, v[66:67]
	v_add_f32_e32 v178, 1.0, v178
	v_rcp_f32_e32 v178, v178
	v_mul_f32_e32 v34, v34, v171
	v_mul_f32_e32 v18, v18, v171
	v_mul_f32_e32 v2, v2, v171
	v_mul_f32_e32 v50, v50, v178
	v_bfe_u32 v178, v50, 16, 1
	v_add3_u32 v50, v50, v178, s63
	global_store_short_d16_hi v[98:99], v50, off
	v_lshlrev_b32_e32 v50, 16, v177
	v_mul_f32_e32 v34, v34, v50
	v_mul_f32_e32 v50, 0xbfb8aa3b, v50
	v_exp_f32_e32 v50, v50
	v_mul_f32_e32 v3, v3, v166
	v_mul_f32_e32 v4, v4, v161
	v_mul_f32_e32 v5, v5, v155
	v_add_f32_e32 v50, 1.0, v50
	v_rcp_f32_e32 v50, v50
	s_mov_b32 s74, s8
	v_mul_f32_e32 v34, v34, v50
	v_bfe_u32 v50, v34, 16, 1
	v_add3_u32 v34, v34, v50, s63
	global_store_short_d16_hi v[98:99], v34, off offset:64
	s_waitcnt vmcnt(62)
	v_lshlrev_b32_e32 v34, 16, v176
	v_mul_f32_e32 v18, v18, v34
	v_mul_f32_e32 v34, 0xbfb8aa3b, v34
	v_exp_f32_e32 v34, v34
	v_add_co_u32_e32 v98, vcc, s93, v98
	v_add_f32_e32 v34, 1.0, v34
	v_rcp_f32_e32 v34, v34
	v_addc_co_u32_e32 v99, vcc, 0, v99, vcc
	v_mul_f32_e32 v18, v18, v34
	v_bfe_u32 v34, v18, 16, 1
	v_add3_u32 v18, v18, v34, s63
	global_store_short_d16_hi v[98:99], v18, off
	v_lshlrev_b32_e32 v18, 16, v175
	v_mul_f32_e32 v2, v2, v18
	v_mul_f32_e32 v18, 0xbfb8aa3b, v18
	v_exp_f32_e32 v18, v18
	s_nop 0
	v_add_f32_e32 v18, 1.0, v18
	v_rcp_f32_e32 v18, v18
	s_nop 0
	v_mul_f32_e32 v2, v2, v18
	v_bfe_u32 v18, v2, 16, 1
	v_add3_u32 v2, v2, v18, s63
	global_store_short_d16_hi v[98:99], v2, off offset:64
	s_waitcnt vmcnt(62)
	v_lshlrev_b32_e32 v2, 16, v174
	v_mul_f32_e32 v18, v51, v166
	v_mul_f32_e32 v18, v18, v2
	v_mul_f32_e32 v2, 0xbfb8aa3b, v2
	v_exp_f32_e32 v2, v2
	v_lshlrev_b64 v[50:51], 7, v[96:97]
	v_lshl_add_u64 v[50:51], s[40:41], 0, v[50:51]
	v_lshl_add_u64 v[50:51], v[50:51], 0, v[66:67]
	v_add_f32_e32 v2, 1.0, v2
	v_rcp_f32_e32 v2, v2
	s_nop 0
	v_mul_f32_e32 v2, v18, v2
	v_bfe_u32 v18, v2, 16, 1
	v_add3_u32 v2, v2, v18, s63
	global_store_short_d16_hi v[50:51], v2, off
	v_lshlrev_b32_e32 v2, 16, v173
	v_mul_f32_e32 v18, v35, v166
	v_mul_f32_e32 v18, v18, v2
	v_mul_f32_e32 v2, 0xbfb8aa3b, v2
	v_exp_f32_e32 v2, v2
	s_nop 0
	v_add_f32_e32 v2, 1.0, v2
	v_rcp_f32_e32 v2, v2
	s_nop 0
	v_mul_f32_e32 v2, v18, v2
	v_bfe_u32 v18, v2, 16, 1
	v_add3_u32 v2, v2, v18, s63
	global_store_short_d16_hi v[50:51], v2, off offset:64
	s_waitcnt vmcnt(62)
	v_lshlrev_b32_e32 v2, 16, v172
	v_mul_f32_e32 v18, v19, v166
	v_mul_f32_e32 v18, v18, v2
	v_mul_f32_e32 v2, 0xbfb8aa3b, v2
	v_exp_f32_e32 v2, v2
	s_nop 0
	v_add_f32_e32 v2, 1.0, v2
	v_rcp_f32_e32 v2, v2
	s_nop 0
	v_mul_f32_e32 v2, v18, v2
	v_bfe_u32 v18, v2, 16, 1
	v_add3_u32 v2, v2, v18, s63
	v_add_co_u32_e32 v18, vcc, s93, v50
	s_nop 1
	v_addc_co_u32_e32 v19, vcc, 0, v51, vcc
	global_store_short_d16_hi v[18:19], v2, off
	v_lshlrev_b32_e32 v2, 16, v170
	v_mul_f32_e32 v3, v3, v2
	v_mul_f32_e32 v2, 0xbfb8aa3b, v2
	v_exp_f32_e32 v2, v2
	s_nop 0
	v_add_f32_e32 v2, 1.0, v2
	v_rcp_f32_e32 v2, v2
	s_nop 0
	v_mul_f32_e32 v2, v3, v2
	v_bfe_u32 v3, v2, 16, 1
	v_add3_u32 v2, v2, v3, s63
	global_store_short_d16_hi v[18:19], v2, off offset:64
	s_waitcnt vmcnt(62)
	v_lshlrev_b32_e32 v2, 16, v169
	v_mul_f32_e32 v3, v52, v161
	v_mul_f32_e32 v3, v3, v2
	v_mul_f32_e32 v2, 0xbfb8aa3b, v2
	v_exp_f32_e32 v2, v2
	v_mul_f32_e32 v19, v36, v161
	v_add_f32_e32 v2, 1.0, v2
	v_rcp_f32_e32 v2, v2
	s_nop 0
	v_mul_f32_e32 v2, v3, v2
	v_bfe_u32 v3, v2, 16, 1
	v_add3_u32 v18, v2, v3, s63
	v_lshlrev_b64 v[2:3], 7, v[94:95]
	v_lshl_add_u64 v[2:3], s[40:41], 0, v[2:3]
	v_lshl_add_u64 v[2:3], v[2:3], 0, v[66:67]
	global_store_short_d16_hi v[2:3], v18, off
	v_lshlrev_b32_e32 v18, 16, v168
	v_mul_f32_e32 v19, v19, v18
	v_mul_f32_e32 v18, 0xbfb8aa3b, v18
	v_exp_f32_e32 v18, v18
	s_nop 0
	v_add_f32_e32 v18, 1.0, v18
	v_rcp_f32_e32 v18, v18
	s_nop 0
	v_mul_f32_e32 v18, v19, v18
	v_bfe_u32 v19, v18, 16, 1
	v_add3_u32 v18, v18, v19, s63
	global_store_short_d16_hi v[2:3], v18, off offset:64
	s_waitcnt vmcnt(62)
	v_lshlrev_b32_e32 v18, 16, v167
	v_mul_f32_e32 v19, v20, v161
	v_mul_f32_e32 v19, v19, v18
	v_mul_f32_e32 v18, 0xbfb8aa3b, v18
	v_exp_f32_e32 v18, v18
	v_add_co_u32_e32 v2, vcc, s93, v2
	v_add_f32_e32 v18, 1.0, v18
	v_rcp_f32_e32 v18, v18
	v_addc_co_u32_e32 v3, vcc, 0, v3, vcc
	v_mul_f32_e32 v18, v19, v18
	v_bfe_u32 v19, v18, 16, 1
	v_add3_u32 v18, v18, v19, s63
	global_store_short_d16_hi v[2:3], v18, off
	v_lshlrev_b32_e32 v18, 16, v165
	v_mul_f32_e32 v4, v4, v18
	v_mul_f32_e32 v18, 0xbfb8aa3b, v18
	v_exp_f32_e32 v18, v18
	s_nop 0
	v_add_f32_e32 v18, 1.0, v18
	v_rcp_f32_e32 v18, v18
	s_nop 0
	v_mul_f32_e32 v4, v4, v18
	v_bfe_u32 v18, v4, 16, 1
	v_add3_u32 v4, v4, v18, s63
	global_store_short_d16_hi v[2:3], v4, off offset:64
	s_waitcnt vmcnt(62)
	v_lshlrev_b32_e32 v2, 16, v164
	v_mul_f32_e32 v3, v53, v155
	v_mul_f32_e32 v3, v3, v2
	v_mul_f32_e32 v2, 0xbfb8aa3b, v2
	v_exp_f32_e32 v2, v2
	v_mul_f32_e32 v18, v37, v155
	v_add_f32_e32 v2, 1.0, v2
	v_rcp_f32_e32 v2, v2
	s_nop 0
	v_mul_f32_e32 v2, v3, v2
	v_bfe_u32 v3, v2, 16, 1
	v_add3_u32 v4, v2, v3, s63
	v_lshlrev_b64 v[2:3], 7, v[92:93]
	v_lshl_add_u64 v[2:3], s[40:41], 0, v[2:3]
	v_lshl_add_u64 v[2:3], v[2:3], 0, v[66:67]
	global_store_short_d16_hi v[2:3], v4, off
	v_lshlrev_b32_e32 v4, 16, v163
	v_mul_f32_e32 v18, v18, v4
	v_mul_f32_e32 v4, 0xbfb8aa3b, v4
	v_exp_f32_e32 v4, v4
	s_nop 0
	v_add_f32_e32 v4, 1.0, v4
	v_rcp_f32_e32 v4, v4
	s_nop 0
	v_mul_f32_e32 v4, v18, v4
	v_bfe_u32 v18, v4, 16, 1
	v_add3_u32 v4, v4, v18, s63
	global_store_short_d16_hi v[2:3], v4, off offset:64
	s_waitcnt vmcnt(62)
; __device__ __forceinline__ float bf2f(unsigned h) { return __uint_as_float(h << 16); }
; __device__ __forceinline__ unsigned f2bf(float f) { unsigned u = __float_as_uint(f); return (u + 0x7fffu + ((u >> 16) & 1u)) >> 16; }
; __device__ __forceinline__ int crow(int r, int hi) { return (r & 3) + 8 * (r >> 2) + 4 * hi; }
; __device__ __forceinline__ void mla_unit(char* lds, const bf16_t* __restrict__ Qp, const bf16_t* __restrict__ Knp, const bf16_t* __restrict__ Vp, ...
;     ...
; #pragma unroll
;     for (int r = 0; r < 16; ++r) { const long trow = wid * QBLK + crow(r, hi);
; #pragma unroll
;       for (int d0 = 0; d0 < 4; ++d0) { const float z = bf2f(zr[r][d0]); const float v = o[d0][r] * rli[r];
;         const float g = v * z * __builtin_amdgcn_rcpf(1.f + __expf(-z));
;         Op[((size_t)(d0 >> 1) * M_TOK + trow) * 64 + (d0 & 1) * 32 + r32] = (bf16_t)f2bf(g); } } }
	v_lshlrev_b32_e32 v4, 16, v162
	v_mul_f32_e32 v18, v21, v155
	v_mul_f32_e32 v18, v18, v4
	v_mul_f32_e32 v4, 0xbfb8aa3b, v4
	v_exp_f32_e32 v4, v4
	v_add_co_u32_e32 v2, vcc, s93, v2
	v_add_f32_e32 v4, 1.0, v4
	v_rcp_f32_e32 v4, v4
	v_addc_co_u32_e32 v3, vcc, 0, v3, vcc
	v_mul_f32_e32 v4, v18, v4
	v_bfe_u32 v18, v4, 16, 1
	v_add3_u32 v4, v4, v18, s63
	global_store_short_d16_hi v[2:3], v4, off
	v_lshlrev_b32_e32 v4, 16, v160
	v_mul_f32_e32 v5, v5, v4
	v_mul_f32_e32 v4, 0xbfb8aa3b, v4
	v_exp_f32_e32 v4, v4
	s_nop 0
	v_add_f32_e32 v4, 1.0, v4
	v_rcp_f32_e32 v4, v4
	s_nop 0
	v_mul_f32_e32 v4, v5, v4
	v_bfe_u32 v5, v4, 16, 1
	v_add3_u32 v4, v4, v5, s63
	global_store_short_d16_hi v[2:3], v4, off offset:64
	s_waitcnt vmcnt(62)
	v_lshlrev_b32_e32 v2, 16, v159
	v_mul_f32_e32 v3, v54, v150
	v_mul_f32_e32 v3, v3, v2
	v_mul_f32_e32 v2, 0xbfb8aa3b, v2
	v_exp_f32_e32 v2, v2
	v_mul_f32_e32 v5, v38, v150
	v_add_f32_e32 v2, 1.0, v2
	v_rcp_f32_e32 v2, v2
	s_nop 0
	v_mul_f32_e32 v2, v3, v2
	v_bfe_u32 v3, v2, 16, 1
	v_add3_u32 v4, v2, v3, s63
	v_lshlrev_b64 v[2:3], 7, v[90:91]
	v_lshl_add_u64 v[2:3], s[40:41], 0, v[2:3]
	v_lshl_add_u64 v[2:3], v[2:3], 0, v[66:67]
	global_store_short_d16_hi v[2:3], v4, off
	v_lshlrev_b32_e32 v4, 16, v158
	v_mul_f32_e32 v5, v5, v4
	v_mul_f32_e32 v4, 0xbfb8aa3b, v4
	v_exp_f32_e32 v4, v4
	s_nop 0
	v_add_f32_e32 v4, 1.0, v4
	v_rcp_f32_e32 v4, v4
	s_nop 0
	v_mul_f32_e32 v4, v5, v4
	v_bfe_u32 v5, v4, 16, 1
	v_add3_u32 v4, v4, v5, s63
	global_store_short_d16_hi v[2:3], v4, off offset:64
	s_waitcnt vmcnt(62)
	v_lshlrev_b32_e32 v4, 16, v157
	v_mul_f32_e32 v5, v22, v150
	v_mul_f32_e32 v5, v5, v4
	v_mul_f32_e32 v4, 0xbfb8aa3b, v4
	v_exp_f32_e32 v4, v4
	v_add_co_u32_e32 v2, vcc, s93, v2
	v_add_f32_e32 v4, 1.0, v4
	v_rcp_f32_e32 v4, v4
	v_addc_co_u32_e32 v3, vcc, 0, v3, vcc
	v_mul_f32_e32 v4, v5, v4
	v_bfe_u32 v5, v4, 16, 1
	v_add3_u32 v4, v4, v5, s63
	global_store_short_d16_hi v[2:3], v4, off
	v_lshlrev_b32_e32 v4, 16, v156
	v_mul_f32_e32 v5, v6, v150
	v_mul_f32_e32 v5, v5, v4
	v_mul_f32_e32 v4, 0xbfb8aa3b, v4
	v_exp_f32_e32 v4, v4
	s_nop 0
	v_add_f32_e32 v4, 1.0, v4
	v_rcp_f32_e32 v4, v4
	s_nop 0
	v_mul_f32_e32 v4, v5, v4
	v_bfe_u32 v5, v4, 16, 1
	v_add3_u32 v4, v4, v5, s63
	global_store_short_d16_hi v[2:3], v4, off offset:64
	s_waitcnt vmcnt(62)
	v_lshlrev_b32_e32 v2, 16, v154
	v_mul_f32_e32 v3, v55, v144
	v_mul_f32_e32 v3, v3, v2
	v_mul_f32_e32 v2, 0xbfb8aa3b, v2
	v_exp_f32_e32 v2, v2
	v_mul_f32_e32 v5, v39, v144
	v_add_f32_e32 v2, 1.0, v2
	v_rcp_f32_e32 v2, v2
	s_nop 0
	v_mul_f32_e32 v2, v3, v2
	v_bfe_u32 v3, v2, 16, 1
	v_add3_u32 v4, v2, v3, s63
	v_lshlrev_b64 v[2:3], 7, v[88:89]
	v_lshl_add_u64 v[2:3], s[40:41], 0, v[2:3]
	v_lshl_add_u64 v[2:3], v[2:3], 0, v[66:67]
	global_store_short_d16_hi v[2:3], v4, off
	v_lshlrev_b32_e32 v4, 16, v153
	v_mul_f32_e32 v5, v5, v4
	v_mul_f32_e32 v4, 0xbfb8aa3b, v4
	v_exp_f32_e32 v4, v4
	s_nop 0
	v_add_f32_e32 v4, 1.0, v4
	v_rcp_f32_e32 v4, v4
	s_nop 0
	v_mul_f32_e32 v4, v5, v4
	v_bfe_u32 v5, v4, 16, 1
	v_add3_u32 v4, v4, v5, s63
	global_store_short_d16_hi v[2:3], v4, off offset:64
	s_waitcnt vmcnt(62)
	v_lshlrev_b32_e32 v4, 16, v152
	v_mul_f32_e32 v5, v23, v144
	v_mul_f32_e32 v5, v5, v4
	v_mul_f32_e32 v4, 0xbfb8aa3b, v4
	v_exp_f32_e32 v4, v4
	v_add_co_u32_e32 v2, vcc, s93, v2
	v_add_f32_e32 v4, 1.0, v4
	v_rcp_f32_e32 v4, v4
	v_addc_co_u32_e32 v3, vcc, 0, v3, vcc
	v_mul_f32_e32 v4, v5, v4
	v_bfe_u32 v5, v4, 16, 1
	v_add3_u32 v4, v4, v5, s63
	global_store_short_d16_hi v[2:3], v4, off
	v_lshlrev_b32_e32 v4, 16, v151
	v_mul_f32_e32 v5, v7, v144
	v_mul_f32_e32 v5, v5, v4
	v_mul_f32_e32 v4, 0xbfb8aa3b, v4
	v_exp_f32_e32 v4, v4
	s_nop 0
	v_add_f32_e32 v4, 1.0, v4
	v_rcp_f32_e32 v4, v4
	s_nop 0
	v_mul_f32_e32 v4, v5, v4
	v_bfe_u32 v5, v4, 16, 1
	v_add3_u32 v4, v4, v5, s63
	global_store_short_d16_hi v[2:3], v4, off offset:64
	s_waitcnt vmcnt(62)
	v_lshlrev_b32_e32 v2, 16, v149
	v_mul_f32_e32 v3, v56, v139
	v_mul_f32_e32 v3, v3, v2
	v_mul_f32_e32 v2, 0xbfb8aa3b, v2
	v_exp_f32_e32 v2, v2
	v_mul_f32_e32 v5, v40, v139
	v_add_f32_e32 v2, 1.0, v2
	v_rcp_f32_e32 v2, v2
	s_nop 0
	v_mul_f32_e32 v2, v3, v2
	v_bfe_u32 v3, v2, 16, 1
	v_add3_u32 v4, v2, v3, s63
	v_lshlrev_b64 v[2:3], 7, v[86:87]
	v_lshl_add_u64 v[2:3], s[40:41], 0, v[2:3]
	v_lshl_add_u64 v[2:3], v[2:3], 0, v[66:67]
	global_store_short_d16_hi v[2:3], v4, off
	v_lshlrev_b32_e32 v4, 16, v148
	v_mul_f32_e32 v5, v5, v4
	v_mul_f32_e32 v4, 0xbfb8aa3b, v4
	v_exp_f32_e32 v4, v4
	s_nop 0
	v_add_f32_e32 v4, 1.0, v4
	v_rcp_f32_e32 v4, v4
	s_nop 0
	v_mul_f32_e32 v4, v5, v4
	v_bfe_u32 v5, v4, 16, 1
	v_add3_u32 v4, v4, v5, s63
	global_store_short_d16_hi v[2:3], v4, off offset:64
	s_waitcnt vmcnt(62)
	v_lshlrev_b32_e32 v4, 16, v147
	v_mul_f32_e32 v5, v24, v139
	v_mul_f32_e32 v5, v5, v4
	v_mul_f32_e32 v4, 0xbfb8aa3b, v4
	v_exp_f32_e32 v4, v4
	v_add_co_u32_e32 v2, vcc, s93, v2
	v_add_f32_e32 v4, 1.0, v4
	v_rcp_f32_e32 v4, v4
	v_addc_co_u32_e32 v3, vcc, 0, v3, vcc
	v_mul_f32_e32 v4, v5, v4
	v_bfe_u32 v5, v4, 16, 1
	v_add3_u32 v4, v4, v5, s63
	global_store_short_d16_hi v[2:3], v4, off
	v_lshlrev_b32_e32 v4, 16, v146
	v_mul_f32_e32 v5, v8, v139
	v_mul_f32_e32 v5, v5, v4
	v_mul_f32_e32 v4, 0xbfb8aa3b, v4
	v_exp_f32_e32 v4, v4
	s_nop 0
	v_add_f32_e32 v4, 1.0, v4
	v_rcp_f32_e32 v4, v4
	s_nop 0
	v_mul_f32_e32 v4, v5, v4
	v_bfe_u32 v5, v4, 16, 1
	v_add3_u32 v4, v4, v5, s63
	global_store_short_d16_hi v[2:3], v4, off offset:64
	s_waitcnt vmcnt(62)
; __device__ __forceinline__ float bf2f(unsigned h) { return __uint_as_float(h << 16); }
; __device__ __forceinline__ unsigned f2bf(float f) { unsigned u = __float_as_uint(f); return (u + 0x7fffu + ((u >> 16) & 1u)) >> 16; }
; __device__ __forceinline__ int crow(int r, int hi) { return (r & 3) + 8 * (r >> 2) + 4 * hi; }
; __device__ __forceinline__ void mla_unit(char* lds, const bf16_t* __restrict__ Qp, const bf16_t* __restrict__ Knp, const bf16_t* __restrict__ Vp, ...
;     ...
; #pragma unroll
;     for (int r = 0; r < 16; ++r) { const long trow = wid * QBLK + crow(r, hi);
; #pragma unroll
;       for (int d0 = 0; d0 < 4; ++d0) { const float z = bf2f(zr[r][d0]); const float v = o[d0][r] * rli[r];
;         const float g = v * z * __builtin_amdgcn_rcpf(1.f + __expf(-z));
;         Op[((size_t)(d0 >> 1) * M_TOK + trow) * 64 + (d0 & 1) * 32 + r32] = (bf16_t)f2bf(g); } } }
	v_lshlrev_b32_e32 v2, 16, v145
	v_mul_f32_e32 v3, v57, v133
	v_mul_f32_e32 v3, v3, v2
	v_mul_f32_e32 v2, 0xbfb8aa3b, v2
	v_exp_f32_e32 v2, v2
	v_mul_f32_e32 v5, v41, v133
	v_add_f32_e32 v2, 1.0, v2
	v_rcp_f32_e32 v2, v2
	s_nop 0
	v_mul_f32_e32 v2, v3, v2
	v_bfe_u32 v3, v2, 16, 1
	v_add3_u32 v4, v2, v3, s63
	v_lshlrev_b64 v[2:3], 7, v[84:85]
	v_lshl_add_u64 v[2:3], s[40:41], 0, v[2:3]
	v_lshl_add_u64 v[2:3], v[2:3], 0, v[66:67]
	global_store_short_d16_hi v[2:3], v4, off
	v_lshlrev_b32_e32 v4, 16, v143
	v_mul_f32_e32 v5, v5, v4
	v_mul_f32_e32 v4, 0xbfb8aa3b, v4
	v_exp_f32_e32 v4, v4
	s_nop 0
	v_add_f32_e32 v4, 1.0, v4
	v_rcp_f32_e32 v4, v4
	s_nop 0
	v_mul_f32_e32 v4, v5, v4
	v_bfe_u32 v5, v4, 16, 1
	v_add3_u32 v4, v4, v5, s63
	global_store_short_d16_hi v[2:3], v4, off offset:64
	s_waitcnt vmcnt(62)
	v_lshlrev_b32_e32 v4, 16, v142
	v_mul_f32_e32 v5, v25, v133
	v_mul_f32_e32 v5, v5, v4
	v_mul_f32_e32 v4, 0xbfb8aa3b, v4
	v_exp_f32_e32 v4, v4
	v_add_co_u32_e32 v2, vcc, s93, v2
	v_add_f32_e32 v4, 1.0, v4
	v_rcp_f32_e32 v4, v4
	v_addc_co_u32_e32 v3, vcc, 0, v3, vcc
	v_mul_f32_e32 v4, v5, v4
	v_bfe_u32 v5, v4, 16, 1
	v_add3_u32 v4, v4, v5, s63
	global_store_short_d16_hi v[2:3], v4, off
	v_lshlrev_b32_e32 v4, 16, v141
	v_mul_f32_e32 v5, v9, v133
	v_mul_f32_e32 v5, v5, v4
	v_mul_f32_e32 v4, 0xbfb8aa3b, v4
	v_exp_f32_e32 v4, v4
	s_nop 0
	v_add_f32_e32 v4, 1.0, v4
	v_rcp_f32_e32 v4, v4
	s_nop 0
	v_mul_f32_e32 v4, v5, v4
	v_bfe_u32 v5, v4, 16, 1
	v_add3_u32 v4, v4, v5, s63
	global_store_short_d16_hi v[2:3], v4, off offset:64
	s_waitcnt vmcnt(62)
	v_lshlrev_b32_e32 v2, 16, v140
	v_mul_f32_e32 v3, v58, v128
	v_mul_f32_e32 v3, v3, v2
	v_mul_f32_e32 v2, 0xbfb8aa3b, v2
	v_exp_f32_e32 v2, v2
	v_mul_f32_e32 v5, v42, v128
	v_add_f32_e32 v2, 1.0, v2
	v_rcp_f32_e32 v2, v2
	s_nop 0
	v_mul_f32_e32 v2, v3, v2
	v_bfe_u32 v3, v2, 16, 1
	v_add3_u32 v4, v2, v3, s63
	v_lshlrev_b64 v[2:3], 7, v[82:83]
	v_lshl_add_u64 v[2:3], s[40:41], 0, v[2:3]
	v_lshl_add_u64 v[2:3], v[2:3], 0, v[66:67]
	global_store_short_d16_hi v[2:3], v4, off
	v_lshlrev_b32_e32 v4, 16, v138
	v_mul_f32_e32 v5, v5, v4
	v_mul_f32_e32 v4, 0xbfb8aa3b, v4
	v_exp_f32_e32 v4, v4
	s_nop 0
	v_add_f32_e32 v4, 1.0, v4
	v_rcp_f32_e32 v4, v4
	s_nop 0
	v_mul_f32_e32 v4, v5, v4
	v_bfe_u32 v5, v4, 16, 1
	v_add3_u32 v4, v4, v5, s63
	global_store_short_d16_hi v[2:3], v4, off offset:64
	s_waitcnt vmcnt(62)
	v_lshlrev_b32_e32 v4, 16, v137
	v_mul_f32_e32 v5, v26, v128
	v_mul_f32_e32 v5, v5, v4
	v_mul_f32_e32 v4, 0xbfb8aa3b, v4
	v_exp_f32_e32 v4, v4
	v_add_co_u32_e32 v2, vcc, s93, v2
	v_add_f32_e32 v4, 1.0, v4
	v_rcp_f32_e32 v4, v4
	v_addc_co_u32_e32 v3, vcc, 0, v3, vcc
	v_mul_f32_e32 v4, v5, v4
	v_bfe_u32 v5, v4, 16, 1
	v_add3_u32 v4, v4, v5, s63
	global_store_short_d16_hi v[2:3], v4, off
	v_lshlrev_b32_e32 v4, 16, v136
	v_mul_f32_e32 v5, v10, v128
	v_mul_f32_e32 v5, v5, v4
	v_mul_f32_e32 v4, 0xbfb8aa3b, v4
	v_exp_f32_e32 v4, v4
	s_nop 0
	v_add_f32_e32 v4, 1.0, v4
	v_rcp_f32_e32 v4, v4
	s_nop 0
	v_mul_f32_e32 v4, v5, v4
	v_bfe_u32 v5, v4, 16, 1
	v_add3_u32 v4, v4, v5, s63
	global_store_short_d16_hi v[2:3], v4, off offset:64
	s_waitcnt vmcnt(62)
	v_lshlrev_b32_e32 v2, 16, v135
	v_mul_f32_e32 v3, v59, v122
	v_mul_f32_e32 v3, v3, v2
	v_mul_f32_e32 v2, 0xbfb8aa3b, v2
	v_exp_f32_e32 v2, v2
	v_mul_f32_e32 v5, v43, v122
	v_add_f32_e32 v2, 1.0, v2
	v_rcp_f32_e32 v2, v2
	s_nop 0
	v_mul_f32_e32 v2, v3, v2
	v_bfe_u32 v3, v2, 16, 1
	v_add3_u32 v4, v2, v3, s63
	v_lshlrev_b64 v[2:3], 7, v[80:81]
	v_lshl_add_u64 v[2:3], s[40:41], 0, v[2:3]
	v_lshl_add_u64 v[2:3], v[2:3], 0, v[66:67]
	global_store_short_d16_hi v[2:3], v4, off
	v_lshlrev_b32_e32 v4, 16, v134
	v_mul_f32_e32 v5, v5, v4
	v_mul_f32_e32 v4, 0xbfb8aa3b, v4
	v_exp_f32_e32 v4, v4
	s_nop 0
	v_add_f32_e32 v4, 1.0, v4
	v_rcp_f32_e32 v4, v4
	s_nop 0
	v_mul_f32_e32 v4, v5, v4
	v_bfe_u32 v5, v4, 16, 1
	v_add3_u32 v4, v4, v5, s63
	global_store_short_d16_hi v[2:3], v4, off offset:64
	s_waitcnt vmcnt(62)
	v_lshlrev_b32_e32 v4, 16, v132
	v_mul_f32_e32 v5, v27, v122
	v_mul_f32_e32 v5, v5, v4
	v_mul_f32_e32 v4, 0xbfb8aa3b, v4
	v_exp_f32_e32 v4, v4
	v_add_co_u32_e32 v2, vcc, s93, v2
	v_add_f32_e32 v4, 1.0, v4
	v_rcp_f32_e32 v4, v4
	v_addc_co_u32_e32 v3, vcc, 0, v3, vcc
	v_mul_f32_e32 v4, v5, v4
	v_bfe_u32 v5, v4, 16, 1
	v_add3_u32 v4, v4, v5, s63
	global_store_short_d16_hi v[2:3], v4, off
	v_lshlrev_b32_e32 v4, 16, v131
	v_mul_f32_e32 v5, v11, v122
	v_mul_f32_e32 v5, v5, v4
	v_mul_f32_e32 v4, 0xbfb8aa3b, v4
	v_exp_f32_e32 v4, v4
	s_nop 0
	v_add_f32_e32 v4, 1.0, v4
	v_rcp_f32_e32 v4, v4
	s_nop 0
	v_mul_f32_e32 v4, v5, v4
	v_bfe_u32 v5, v4, 16, 1
	v_add3_u32 v4, v4, v5, s63
	global_store_short_d16_hi v[2:3], v4, off offset:64
	s_waitcnt vmcnt(62)
	v_lshlrev_b32_e32 v2, 16, v130
	v_mul_f32_e32 v3, v60, v117
	v_mul_f32_e32 v3, v3, v2
	v_mul_f32_e32 v2, 0xbfb8aa3b, v2
	v_exp_f32_e32 v2, v2
	v_mul_f32_e32 v5, v44, v117
	v_add_f32_e32 v2, 1.0, v2
	v_rcp_f32_e32 v2, v2
	s_nop 0
	v_mul_f32_e32 v2, v3, v2
	v_bfe_u32 v3, v2, 16, 1
	v_add3_u32 v4, v2, v3, s63
	v_lshlrev_b64 v[2:3], 7, v[78:79]
	v_lshl_add_u64 v[2:3], s[40:41], 0, v[2:3]
	v_lshl_add_u64 v[2:3], v[2:3], 0, v[66:67]
	global_store_short_d16_hi v[2:3], v4, off
	v_lshlrev_b32_e32 v4, 16, v129
	v_mul_f32_e32 v5, v5, v4
	v_mul_f32_e32 v4, 0xbfb8aa3b, v4
	v_exp_f32_e32 v4, v4
	s_nop 0
	v_add_f32_e32 v4, 1.0, v4
	v_rcp_f32_e32 v4, v4
	s_nop 0
	v_mul_f32_e32 v4, v5, v4
	v_bfe_u32 v5, v4, 16, 1
	v_add3_u32 v4, v4, v5, s63
	global_store_short_d16_hi v[2:3], v4, off offset:64
	s_waitcnt vmcnt(62)
; __device__ __forceinline__ float bf2f(unsigned h) { return __uint_as_float(h << 16); }
; __device__ __forceinline__ unsigned f2bf(float f) { unsigned u = __float_as_uint(f); return (u + 0x7fffu + ((u >> 16) & 1u)) >> 16; }
; __device__ __forceinline__ int crow(int r, int hi) { return (r & 3) + 8 * (r >> 2) + 4 * hi; }
; __device__ __forceinline__ void mla_unit(char* lds, const bf16_t* __restrict__ Qp, const bf16_t* __restrict__ Knp, const bf16_t* __restrict__ Vp, ...
;     ...
; #pragma unroll
;     for (int r = 0; r < 16; ++r) { const long trow = wid * QBLK + crow(r, hi);
; #pragma unroll
;       for (int d0 = 0; d0 < 4; ++d0) { const float z = bf2f(zr[r][d0]); const float v = o[d0][r] * rli[r];
;         const float g = v * z * __builtin_amdgcn_rcpf(1.f + __expf(-z));
;         Op[((size_t)(d0 >> 1) * M_TOK + trow) * 64 + (d0 & 1) * 32 + r32] = (bf16_t)f2bf(g); } } }
	v_lshlrev_b32_e32 v4, 16, v127
	v_mul_f32_e32 v5, v28, v117
	v_mul_f32_e32 v5, v5, v4
	v_mul_f32_e32 v4, 0xbfb8aa3b, v4
	v_exp_f32_e32 v4, v4
	v_add_co_u32_e32 v2, vcc, s93, v2
	v_add_f32_e32 v4, 1.0, v4
	v_rcp_f32_e32 v4, v4
	v_addc_co_u32_e32 v3, vcc, 0, v3, vcc
	v_mul_f32_e32 v4, v5, v4
	v_bfe_u32 v5, v4, 16, 1
	v_add3_u32 v4, v4, v5, s63
	global_store_short_d16_hi v[2:3], v4, off
	v_lshlrev_b32_e32 v4, 16, v126
	v_mul_f32_e32 v5, v12, v117
	v_mul_f32_e32 v5, v5, v4
	v_mul_f32_e32 v4, 0xbfb8aa3b, v4
	v_exp_f32_e32 v4, v4
	s_nop 0
	v_add_f32_e32 v4, 1.0, v4
	v_rcp_f32_e32 v4, v4
	s_nop 0
	v_mul_f32_e32 v4, v5, v4
	v_bfe_u32 v5, v4, 16, 1
	v_add3_u32 v4, v4, v5, s63
	global_store_short_d16_hi v[2:3], v4, off offset:64
	s_waitcnt vmcnt(62)
	v_lshlrev_b32_e32 v2, 16, v125
	v_mul_f32_e32 v3, v61, v111
	v_mul_f32_e32 v3, v3, v2
	v_mul_f32_e32 v2, 0xbfb8aa3b, v2
	v_exp_f32_e32 v2, v2
	v_mul_f32_e32 v5, v45, v111
	v_add_f32_e32 v2, 1.0, v2
	v_rcp_f32_e32 v2, v2
	s_nop 0
	v_mul_f32_e32 v2, v3, v2
	v_bfe_u32 v3, v2, 16, 1
	v_add3_u32 v4, v2, v3, s63
	v_lshlrev_b64 v[2:3], 7, v[76:77]
	v_lshl_add_u64 v[2:3], s[40:41], 0, v[2:3]
	v_lshl_add_u64 v[2:3], v[2:3], 0, v[66:67]
	global_store_short_d16_hi v[2:3], v4, off
	v_lshlrev_b32_e32 v4, 16, v124
	v_mul_f32_e32 v5, v5, v4
	v_mul_f32_e32 v4, 0xbfb8aa3b, v4
	v_exp_f32_e32 v4, v4
	s_nop 0
	v_add_f32_e32 v4, 1.0, v4
	v_rcp_f32_e32 v4, v4
	s_nop 0
	v_mul_f32_e32 v4, v5, v4
	v_bfe_u32 v5, v4, 16, 1
	v_add3_u32 v4, v4, v5, s63
	global_store_short_d16_hi v[2:3], v4, off offset:64
	s_waitcnt vmcnt(62)
	v_lshlrev_b32_e32 v4, 16, v123
	v_mul_f32_e32 v5, v29, v111
	v_mul_f32_e32 v5, v5, v4
	v_mul_f32_e32 v4, 0xbfb8aa3b, v4
	v_exp_f32_e32 v4, v4
	v_add_co_u32_e32 v2, vcc, s93, v2
	v_add_f32_e32 v4, 1.0, v4
	v_rcp_f32_e32 v4, v4
	v_addc_co_u32_e32 v3, vcc, 0, v3, vcc
	v_mul_f32_e32 v4, v5, v4
	v_bfe_u32 v5, v4, 16, 1
	v_add3_u32 v4, v4, v5, s63
	global_store_short_d16_hi v[2:3], v4, off
	v_lshlrev_b32_e32 v4, 16, v121
	v_mul_f32_e32 v5, v13, v111
	v_mul_f32_e32 v5, v5, v4
	v_mul_f32_e32 v4, 0xbfb8aa3b, v4
	v_exp_f32_e32 v4, v4
	s_nop 0
	v_add_f32_e32 v4, 1.0, v4
	v_rcp_f32_e32 v4, v4
	s_nop 0
	v_mul_f32_e32 v4, v5, v4
	v_bfe_u32 v5, v4, 16, 1
	v_add3_u32 v4, v4, v5, s63
	global_store_short_d16_hi v[2:3], v4, off offset:64
	s_waitcnt vmcnt(62)
	v_lshlrev_b32_e32 v2, 16, v120
	v_mul_f32_e32 v3, v62, v105
	v_mul_f32_e32 v3, v3, v2
	v_mul_f32_e32 v2, 0xbfb8aa3b, v2
	v_exp_f32_e32 v2, v2
	v_mul_f32_e32 v5, v46, v105
	v_add_f32_e32 v2, 1.0, v2
	v_rcp_f32_e32 v2, v2
	s_nop 0
	v_mul_f32_e32 v2, v3, v2
	v_bfe_u32 v3, v2, 16, 1
	v_add3_u32 v4, v2, v3, s63
	v_lshlrev_b64 v[2:3], 7, v[74:75]
	v_lshl_add_u64 v[2:3], s[40:41], 0, v[2:3]
	v_lshl_add_u64 v[2:3], v[2:3], 0, v[66:67]
	global_store_short_d16_hi v[2:3], v4, off
	v_lshlrev_b32_e32 v4, 16, v119
	v_mul_f32_e32 v5, v5, v4
	v_mul_f32_e32 v4, 0xbfb8aa3b, v4
	v_exp_f32_e32 v4, v4
	s_nop 0
	v_add_f32_e32 v4, 1.0, v4
	v_rcp_f32_e32 v4, v4
	s_nop 0
	v_mul_f32_e32 v4, v5, v4
	v_bfe_u32 v5, v4, 16, 1
	v_add3_u32 v4, v4, v5, s63
	global_store_short_d16_hi v[2:3], v4, off offset:64
	s_waitcnt vmcnt(62)
	v_lshlrev_b32_e32 v4, 16, v118
	v_mul_f32_e32 v5, v30, v105
	v_mul_f32_e32 v5, v5, v4
	v_mul_f32_e32 v4, 0xbfb8aa3b, v4
	v_exp_f32_e32 v4, v4
	v_add_co_u32_e32 v2, vcc, s93, v2
	v_add_f32_e32 v4, 1.0, v4
	v_rcp_f32_e32 v4, v4
	v_addc_co_u32_e32 v3, vcc, 0, v3, vcc
	v_mul_f32_e32 v4, v5, v4
	v_bfe_u32 v5, v4, 16, 1
	v_add3_u32 v4, v4, v5, s63
	global_store_short_d16_hi v[2:3], v4, off
	v_lshlrev_b32_e32 v4, 16, v116
	v_mul_f32_e32 v5, v14, v105
	v_mul_f32_e32 v5, v5, v4
	v_mul_f32_e32 v4, 0xbfb8aa3b, v4
	v_exp_f32_e32 v4, v4
	s_nop 0
	v_add_f32_e32 v4, 1.0, v4
	v_rcp_f32_e32 v4, v4
	s_nop 0
	v_mul_f32_e32 v4, v5, v4
	v_bfe_u32 v5, v4, 16, 1
	v_add3_u32 v4, v4, v5, s63
	global_store_short_d16_hi v[2:3], v4, off offset:64
	s_waitcnt vmcnt(62)
	v_lshlrev_b32_e32 v2, 16, v115
	v_mul_f32_e32 v3, v63, v103
	v_mul_f32_e32 v3, v3, v2
	v_mul_f32_e32 v2, 0xbfb8aa3b, v2
	v_exp_f32_e32 v2, v2
	v_mul_f32_e32 v5, v47, v103
	v_add_f32_e32 v2, 1.0, v2
	v_rcp_f32_e32 v2, v2
	s_nop 0
	v_mul_f32_e32 v2, v3, v2
	v_bfe_u32 v3, v2, 16, 1
	v_add3_u32 v4, v2, v3, s63
	v_lshlrev_b64 v[2:3], 7, v[72:73]
	v_lshl_add_u64 v[2:3], s[40:41], 0, v[2:3]
	v_lshl_add_u64 v[2:3], v[2:3], 0, v[66:67]
	global_store_short_d16_hi v[2:3], v4, off
	v_lshlrev_b32_e32 v4, 16, v114
	v_mul_f32_e32 v5, v5, v4
	v_mul_f32_e32 v4, 0xbfb8aa3b, v4
	v_exp_f32_e32 v4, v4
	s_nop 0
	v_add_f32_e32 v4, 1.0, v4
	v_rcp_f32_e32 v4, v4
	s_nop 0
	v_mul_f32_e32 v4, v5, v4
	v_bfe_u32 v5, v4, 16, 1
	v_add3_u32 v4, v4, v5, s63
	global_store_short_d16_hi v[2:3], v4, off offset:64
	s_waitcnt vmcnt(62)
; __device__ __forceinline__ float bf2f(unsigned h) { return __uint_as_float(h << 16); }
; __device__ __forceinline__ unsigned f2bf(float f) { unsigned u = __float_as_uint(f); return (u + 0x7fffu + ((u >> 16) & 1u)) >> 16; }
; __device__ __forceinline__ int crow(int r, int hi) { return (r & 3) + 8 * (r >> 2) + 4 * hi; }
; __device__ __forceinline__ void mla_unit(char* lds, const bf16_t* __restrict__ Qp, const bf16_t* __restrict__ Knp, const bf16_t* __restrict__ Vp, ...
;     ...
; #pragma unroll
;     for (int r = 0; r < 16; ++r) { const long trow = wid * QBLK + crow(r, hi);
; #pragma unroll
;       for (int d0 = 0; d0 < 4; ++d0) { const float z = bf2f(zr[r][d0]); const float v = o[d0][r] * rli[r];
;         const float g = v * z * __builtin_amdgcn_rcpf(1.f + __expf(-z));
;         Op[((size_t)(d0 >> 1) * M_TOK + trow) * 64 + (d0 & 1) * 32 + r32] = (bf16_t)f2bf(g); } } }
;   asm volatile("s_waitcnt vmcnt(0) lgkmcnt(0)\n\ts_barrier" ::: "memory");
	v_lshlrev_b32_e32 v4, 16, v113
	v_mul_f32_e32 v5, v31, v103
	v_mul_f32_e32 v5, v5, v4
	v_mul_f32_e32 v4, 0xbfb8aa3b, v4
	v_exp_f32_e32 v4, v4
	v_add_co_u32_e32 v2, vcc, s93, v2
	v_add_f32_e32 v4, 1.0, v4
	v_rcp_f32_e32 v4, v4
	v_addc_co_u32_e32 v3, vcc, 0, v3, vcc
	v_mul_f32_e32 v4, v5, v4
	v_bfe_u32 v5, v4, 16, 1
	v_add3_u32 v4, v4, v5, s63
	global_store_short_d16_hi v[2:3], v4, off
	v_lshlrev_b32_e32 v4, 16, v112
	v_mul_f32_e32 v5, v15, v103
	v_mul_f32_e32 v5, v5, v4
	v_mul_f32_e32 v4, 0xbfb8aa3b, v4
	v_exp_f32_e32 v4, v4
	s_nop 0
	v_add_f32_e32 v4, 1.0, v4
	v_rcp_f32_e32 v4, v4
	s_nop 0
	v_mul_f32_e32 v4, v5, v4
	v_bfe_u32 v5, v4, 16, 1
	v_add3_u32 v4, v4, v5, s63
	global_store_short_d16_hi v[2:3], v4, off offset:64
	s_waitcnt vmcnt(62)
	v_lshlrev_b32_e32 v2, 16, v110
	v_mul_f32_e32 v3, v64, v102
	v_mul_f32_e32 v3, v3, v2
	v_mul_f32_e32 v2, 0xbfb8aa3b, v2
	v_exp_f32_e32 v2, v2
	v_mul_f32_e32 v5, v48, v102
	v_add_f32_e32 v2, 1.0, v2
	v_rcp_f32_e32 v2, v2
	s_nop 0
	v_mul_f32_e32 v2, v3, v2
	v_bfe_u32 v3, v2, 16, 1
	v_add3_u32 v4, v2, v3, s63
	v_lshlrev_b64 v[2:3], 7, v[70:71]
	v_lshl_add_u64 v[2:3], s[40:41], 0, v[2:3]
	v_lshl_add_u64 v[2:3], v[2:3], 0, v[66:67]
	global_store_short_d16_hi v[2:3], v4, off
	v_lshlrev_b32_e32 v4, 16, v109
	v_mul_f32_e32 v5, v5, v4
	v_mul_f32_e32 v4, 0xbfb8aa3b, v4
	v_exp_f32_e32 v4, v4
	s_nop 0
	v_add_f32_e32 v4, 1.0, v4
	v_rcp_f32_e32 v4, v4
	s_nop 0
	v_mul_f32_e32 v4, v5, v4
	v_bfe_u32 v5, v4, 16, 1
	v_add3_u32 v4, v4, v5, s63
	global_store_short_d16_hi v[2:3], v4, off offset:64
	s_waitcnt vmcnt(62)
	v_lshlrev_b32_e32 v4, 16, v108
	v_mul_f32_e32 v5, v32, v102
	v_mul_f32_e32 v5, v5, v4
	v_mul_f32_e32 v4, 0xbfb8aa3b, v4
	v_exp_f32_e32 v4, v4
	v_add_co_u32_e32 v2, vcc, s93, v2
	v_add_f32_e32 v4, 1.0, v4
	v_rcp_f32_e32 v4, v4
	v_addc_co_u32_e32 v3, vcc, 0, v3, vcc
	v_mul_f32_e32 v4, v5, v4
	v_bfe_u32 v5, v4, 16, 1
	v_add3_u32 v4, v4, v5, s63
	global_store_short_d16_hi v[2:3], v4, off
	v_lshlrev_b32_e32 v4, 16, v107
	v_mul_f32_e32 v5, v16, v102
	v_mul_f32_e32 v5, v5, v4
	v_mul_f32_e32 v4, 0xbfb8aa3b, v4
	v_exp_f32_e32 v4, v4
	s_nop 0
	v_add_f32_e32 v4, 1.0, v4
	v_rcp_f32_e32 v4, v4
	s_nop 0
	v_mul_f32_e32 v4, v5, v4
	v_bfe_u32 v5, v4, 16, 1
	v_add3_u32 v4, v4, v5, s63
	global_store_short_d16_hi v[2:3], v4, off offset:64
	s_waitcnt vmcnt(62)
	v_lshlrev_b32_e32 v2, 16, v106
	v_mul_f32_e32 v3, v65, v1
	v_mul_f32_e32 v3, v3, v2
	v_mul_f32_e32 v2, 0xbfb8aa3b, v2
	v_exp_f32_e32 v2, v2
	v_mul_f32_e32 v5, v49, v1
	v_add_f32_e32 v2, 1.0, v2
	v_rcp_f32_e32 v2, v2
	s_nop 0
	v_mul_f32_e32 v2, v3, v2
	v_bfe_u32 v3, v2, 16, 1
	v_add3_u32 v4, v2, v3, s63
	v_lshlrev_b64 v[2:3], 7, v[68:69]
	v_lshl_add_u64 v[2:3], s[40:41], 0, v[2:3]
	v_lshl_add_u64 v[2:3], v[2:3], 0, v[66:67]
	global_store_short_d16_hi v[2:3], v4, off
	v_lshlrev_b32_e32 v4, 16, v104
	v_mul_f32_e32 v5, v5, v4
	v_mul_f32_e32 v4, 0xbfb8aa3b, v4
	v_exp_f32_e32 v4, v4
	s_nop 0
	v_add_f32_e32 v4, 1.0, v4
	v_rcp_f32_e32 v4, v4
	s_nop 0
	v_mul_f32_e32 v4, v5, v4
	v_bfe_u32 v5, v4, 16, 1
	v_add3_u32 v4, v4, v5, s63
	global_store_short_d16_hi v[2:3], v4, off offset:64
	s_waitcnt vmcnt(62)
	v_lshlrev_b32_e32 v4, 16, v101
	v_mul_f32_e32 v5, v33, v1
	v_mul_f32_e32 v5, v5, v4
	v_mul_f32_e32 v4, 0xbfb8aa3b, v4
	v_exp_f32_e32 v4, v4
	v_add_co_u32_e32 v2, vcc, s93, v2
	v_mul_f32_e32 v1, v17, v1
	v_add_f32_e32 v4, 1.0, v4
	v_rcp_f32_e32 v4, v4
	v_addc_co_u32_e32 v3, vcc, 0, v3, vcc
	s_and_b64 vcc, exec, s[42:43]
	v_mul_f32_e32 v4, v5, v4
	v_bfe_u32 v5, v4, 16, 1
	v_add3_u32 v4, v4, v5, s63
	global_store_short_d16_hi v[2:3], v4, off
	v_lshlrev_b32_e32 v4, 16, v100
	v_mul_f32_e32 v1, v1, v4
	v_mul_f32_e32 v4, 0xbfb8aa3b, v4
	v_exp_f32_e32 v4, v4
	s_nop 0
	v_add_f32_e32 v4, 1.0, v4
	v_rcp_f32_e32 v4, v4
	s_nop 0
	v_mul_f32_e32 v1, v1, v4
	v_bfe_u32 v4, v1, 16, 1
	v_add3_u32 v1, v1, v4, s63
	global_store_short_d16_hi v[2:3], v1, off offset:64
	s_setprio 0
	s_waitcnt vmcnt(0) lgkmcnt(0)
	s_barrier
	s_cbranch_vccnz .LBB0_271

; #define SBAR() __builtin_amdgcn_sched_barrier(0)
; __device__ __forceinline__ int crow(int r, int hi) { return (r & 3) + 8 * (r >> 2) + 4 * hi; }
; __device__ __forceinline__ void na_unit3(char* lds, const bf16_t* __restrict__ Qp, const bf16_t* __restrict__ Knp, const bf16_t* __restrict__ Vp, ...
;     ...
;   if (hi == 0) li_l[r32] = l_reg; asm volatile("s_waitcnt lgkmcnt(0)" ::: "memory");
;   float rli[16];
; #pragma unroll
;   for (int r = 0; r < 16; ++r) rli[r] = __builtin_amdgcn_rcpf(li_l[crow(r, hi)]);
;   { unsigned zr[16][4];
; #pragma unroll
;     for (int r = 0; r < 16; ++r) { const long trow = wid * QBLK + crow(r, hi);
; #pragma unroll
;       for (int d0 = 0; d0 < 4; ++d0) zr[r][d0] = Zp[trow * LDZ + d0 * 32 + r32]; }
;     asm volatile("s_waitcnt vmcnt(0)" ::: "memory"); SBAR();
.LBB0_275:
	s_or_b64 exec, exec, s[6:7]
	s_waitcnt lgkmcnt(0)
	v_lshl_add_u32 v1, v222, 4, s26
	ds_read_b128 v[2:5], v1
	ds_read_b128 v[6:9], v1 offset:32
	s_lshl_b64 s[0:1], s[82:83], 1
	s_add_u32 s6, s81, s0
	s_addc_u32 s7, s84, s1
	s_waitcnt lgkmcnt(1)
	v_rcp_f32_e32 v171, v2
	v_rcp_f32_e32 v166, v3
	v_rcp_f32_e32 v161, v4
	v_rcp_f32_e32 v155, v5
	ds_read_b128 v[2:5], v1 offset:64
	s_lshl_b32 s0, s77, 15
	s_add_u32 s0, s34, s0
	s_addc_u32 s1, s35, 0
	s_lshl_b64 s[0:1], s[0:1], 7
	s_waitcnt lgkmcnt(0)
	v_rcp_f32_e32 v128, v2
	v_rcp_f32_e32 v122, v3
	v_rcp_f32_e32 v117, v4
	v_rcp_f32_e32 v111, v5
	ds_read_b128 v[2:5], v1 offset:96
	s_add_u32 s34, s28, s0
	v_lshl_or_b32 v98, v222, 2, s80
	s_addc_u32 s35, s29, s1
	s_mov_b64 s[0:1], 0xc000000
	s_waitcnt lgkmcnt(0)
	v_rcp_f32_e32 v105, v2
	v_rcp_f32_e32 v103, v3
	v_lshlrev_b32_e32 v2, 1, v221
	v_mov_b32_e32 v3, v0
	v_rcp_f32_e32 v102, v4
	v_rcp_f32_e32 v1, v5
	v_lshl_add_u64 v[4:5], s[6:7], 0, v[2:3]
	v_ashrrev_i32_e32 v99, 31, v98
	v_lshl_add_u64 v[100:101], v[4:5], 0, s[0:1]
	v_lshlrev_b64 v[4:5], 9, v[98:99]
	v_or_b32_e32 v96, 1, v98
	v_lshl_add_u64 v[4:5], v[100:101], 0, v[4:5]
	v_ashrrev_i32_e32 v97, 31, v96
	global_load_ushort v180, v[4:5], off nt
	global_load_ushort v177, v[4:5], off offset:64 nt
	global_load_ushort v176, v[4:5], off offset:128 nt
	global_load_ushort v175, v[4:5], off offset:192 nt
	v_lshlrev_b64 v[4:5], 9, v[96:97]
	v_or_b32_e32 v94, 2, v98
	v_lshl_add_u64 v[4:5], v[100:101], 0, v[4:5]
	v_ashrrev_i32_e32 v95, 31, v94
	global_load_ushort v174, v[4:5], off nt
	global_load_ushort v173, v[4:5], off offset:64 nt
	global_load_ushort v172, v[4:5], off offset:128 nt
	global_load_ushort v170, v[4:5], off offset:192 nt
	v_lshlrev_b64 v[4:5], 9, v[94:95]
	v_or_b32_e32 v92, 3, v98
	v_lshl_add_u64 v[4:5], v[100:101], 0, v[4:5]
	v_ashrrev_i32_e32 v93, 31, v92
	global_load_ushort v169, v[4:5], off nt
	global_load_ushort v168, v[4:5], off offset:64 nt
	global_load_ushort v167, v[4:5], off offset:128 nt
	global_load_ushort v165, v[4:5], off offset:192 nt
	v_lshlrev_b64 v[4:5], 9, v[92:93]
	v_or_b32_e32 v90, 8, v98
	v_lshl_add_u64 v[4:5], v[100:101], 0, v[4:5]
	v_ashrrev_i32_e32 v91, 31, v90
	global_load_ushort v164, v[4:5], off nt
	global_load_ushort v163, v[4:5], off offset:64 nt
	global_load_ushort v162, v[4:5], off offset:128 nt
	global_load_ushort v160, v[4:5], off offset:192 nt
	v_lshlrev_b64 v[4:5], 9, v[90:91]
	v_or_b32_e32 v88, 9, v98
	v_lshl_add_u64 v[4:5], v[100:101], 0, v[4:5]
	v_ashrrev_i32_e32 v89, 31, v88
	global_load_ushort v159, v[4:5], off nt
	global_load_ushort v158, v[4:5], off offset:64 nt
	global_load_ushort v157, v[4:5], off offset:128 nt
	global_load_ushort v156, v[4:5], off offset:192 nt
	v_lshlrev_b64 v[4:5], 9, v[88:89]
	v_or_b32_e32 v86, 10, v98
	v_lshl_add_u64 v[4:5], v[100:101], 0, v[4:5]
	v_ashrrev_i32_e32 v87, 31, v86
	global_load_ushort v154, v[4:5], off nt
	global_load_ushort v153, v[4:5], off offset:64 nt
	global_load_ushort v152, v[4:5], off offset:128 nt
	global_load_ushort v151, v[4:5], off offset:192 nt
	v_lshlrev_b64 v[4:5], 9, v[86:87]
	v_or_b32_e32 v84, 11, v98
	v_lshl_add_u64 v[4:5], v[100:101], 0, v[4:5]
	v_ashrrev_i32_e32 v85, 31, v84
	global_load_ushort v150, v[4:5], off nt
	global_load_ushort v148, v[4:5], off offset:64 nt
	global_load_ushort v147, v[4:5], off offset:128 nt
	global_load_ushort v146, v[4:5], off offset:192 nt
	v_lshlrev_b64 v[4:5], 9, v[84:85]
	v_or_b32_e32 v82, 16, v98
	v_lshl_add_u64 v[4:5], v[100:101], 0, v[4:5]
	v_ashrrev_i32_e32 v83, 31, v82
	global_load_ushort v145, v[4:5], off nt
	global_load_ushort v143, v[4:5], off offset:64 nt
	global_load_ushort v142, v[4:5], off offset:128 nt
	global_load_ushort v141, v[4:5], off offset:192 nt
	v_lshlrev_b64 v[4:5], 9, v[82:83]
	v_or_b32_e32 v80, 17, v98
	v_lshl_add_u64 v[4:5], v[100:101], 0, v[4:5]
	v_ashrrev_i32_e32 v81, 31, v80
	global_load_ushort v140, v[4:5], off nt
	global_load_ushort v138, v[4:5], off offset:64 nt
	global_load_ushort v137, v[4:5], off offset:128 nt
	global_load_ushort v136, v[4:5], off offset:192 nt
	v_lshlrev_b64 v[4:5], 9, v[80:81]
	v_or_b32_e32 v14, 18, v98
	v_lshl_add_u64 v[4:5], v[100:101], 0, v[4:5]
	v_ashrrev_i32_e32 v15, 31, v14
	global_load_ushort v135, v[4:5], off nt
	global_load_ushort v134, v[4:5], off offset:64 nt
	global_load_ushort v132, v[4:5], off offset:128 nt
	global_load_ushort v131, v[4:5], off offset:192 nt
	v_lshlrev_b64 v[4:5], 9, v[14:15]
	v_or_b32_e32 v12, 19, v98
	v_lshl_add_u64 v[4:5], v[100:101], 0, v[4:5]
	v_ashrrev_i32_e32 v13, 31, v12
	global_load_ushort v130, v[4:5], off nt
	global_load_ushort v129, v[4:5], off offset:64 nt
	global_load_ushort v127, v[4:5], off offset:128 nt
	global_load_ushort v126, v[4:5], off offset:192 nt
	v_lshlrev_b64 v[4:5], 9, v[12:13]
	v_or_b32_e32 v10, 24, v98
	v_lshl_add_u64 v[4:5], v[100:101], 0, v[4:5]
	v_ashrrev_i32_e32 v11, 31, v10
	v_rcp_f32_e32 v139, v8
	global_load_ushort v125, v[4:5], off nt
	global_load_ushort v124, v[4:5], off offset:64 nt
	global_load_ushort v123, v[4:5], off offset:128 nt
	global_load_ushort v121, v[4:5], off offset:192 nt
	v_lshlrev_b64 v[4:5], 9, v[10:11]
	v_or_b32_e32 v8, 25, v98
	v_rcp_f32_e32 v133, v9
	v_lshl_add_u64 v[4:5], v[100:101], 0, v[4:5]
	v_ashrrev_i32_e32 v9, 31, v8
	v_rcp_f32_e32 v149, v6
	global_load_ushort v120, v[4:5], off nt
	global_load_ushort v119, v[4:5], off offset:64 nt
	global_load_ushort v118, v[4:5], off offset:128 nt
	global_load_ushort v116, v[4:5], off offset:192 nt
	v_lshlrev_b64 v[4:5], 9, v[8:9]
	v_or_b32_e32 v6, 26, v98
	v_rcp_f32_e32 v144, v7
	v_lshl_add_u64 v[4:5], v[100:101], 0, v[4:5]
	v_ashrrev_i32_e32 v7, 31, v6
	global_load_ushort v115, v[4:5], off nt
	global_load_ushort v114, v[4:5], off offset:64 nt
	global_load_ushort v113, v[4:5], off offset:128 nt
	global_load_ushort v112, v[4:5], off offset:192 nt
	v_lshlrev_b64 v[4:5], 9, v[6:7]
	v_lshl_add_u64 v[4:5], v[100:101], 0, v[4:5]
	global_load_ushort v110, v[4:5], off nt
	global_load_ushort v109, v[4:5], off offset:64 nt
	global_load_ushort v108, v[4:5], off offset:128 nt
	global_load_ushort v107, v[4:5], off offset:192 nt
	v_or_b32_e32 v4, 27, v98
	v_ashrrev_i32_e32 v5, 31, v4
	v_lshlrev_b64 v[178:179], 9, v[4:5]
	v_lshl_add_u64 v[178:179], v[100:101], 0, v[178:179]
	global_load_ushort v106, v[178:179], off nt
	global_load_ushort v104, v[178:179], off offset:64 nt
	global_load_ushort v101, v[178:179], off offset:128 nt
	global_load_ushort v100, v[178:179], off offset:192 nt
	s_waitcnt vmcnt(0)
; __device__ __forceinline__ float bf2f(unsigned h) { return __uint_as_float(h << 16); }
; __device__ __forceinline__ unsigned f2bf(float f) { unsigned u = __float_as_uint(f); return (u + 0x7fffu + ((u >> 16) & 1u)) >> 16; }
; __device__ __forceinline__ int crow(int r, int hi) { return (r & 3) + 8 * (r >> 2) + 4 * hi; }
; __device__ __forceinline__ void na_unit3(char* lds, const bf16_t* __restrict__ Qp, const bf16_t* __restrict__ Knp, const bf16_t* __restrict__ Vp, ...
;     ...
; #pragma unroll
;     for (int r = 0; r < 16; ++r) { const long trow = wid * QBLK + crow(r, hi);
; #pragma unroll
;       for (int d0 = 0; d0 < 4; ++d0) { const float z = bf2f(zr[r][d0]); const float v = o[d0][r] * rli[r];
;         const float g = v * z * __builtin_amdgcn_rcpf(1.f + __expf(-z));
;         Op[((size_t)(d0 >> 1) * M_TOK + trow) * 64 + (d0 & 1) * 32 + r32] = (bf16_t)f2bf(g); } } }
	s_waitcnt vmcnt(62)
	v_lshlrev_b32_e32 v178, 16, v180
	v_mul_f32_e32 v64, v64, v171
	v_mul_f32_e32 v64, v64, v178
	v_mul_f32_e32 v178, 0xbfb8aa3b, v178
	v_exp_f32_e32 v178, v178
	v_lshlrev_b64 v[98:99], 7, v[98:99]
	v_lshl_add_u64 v[98:99], s[34:35], 0, v[98:99]
	v_lshl_add_u64 v[98:99], v[98:99], 0, v[2:3]
	v_add_f32_e32 v178, 1.0, v178
	v_rcp_f32_e32 v178, v178
	v_mul_f32_e32 v48, v48, v171
	v_mul_f32_e32 v32, v32, v171
	v_mul_f32_e32 v16, v16, v171
	v_mul_f32_e32 v64, v64, v178
	v_bfe_u32 v178, v64, 16, 1
	v_add3_u32 v64, v64, v178, s63
	global_store_short_d16_hi v[98:99], v64, off
	v_lshlrev_b32_e32 v64, 16, v177
	v_mul_f32_e32 v48, v48, v64
	v_mul_f32_e32 v64, 0xbfb8aa3b, v64
	v_exp_f32_e32 v64, v64
	v_mul_f32_e32 v17, v17, v166
	v_mul_f32_e32 v18, v18, v161
	v_mul_f32_e32 v19, v19, v155
	v_add_f32_e32 v64, 1.0, v64
	v_rcp_f32_e32 v64, v64
	v_lshlrev_b64 v[14:15], 7, v[14:15]
	v_lshl_add_u64 v[14:15], s[34:35], 0, v[14:15]
	v_lshl_add_u64 v[14:15], v[14:15], 0, v[2:3]
	v_mul_f32_e32 v48, v48, v64
	v_bfe_u32 v64, v48, 16, 1
	v_add3_u32 v48, v48, v64, s63
	global_store_short_d16_hi v[98:99], v48, off offset:64
	s_waitcnt vmcnt(62)
	v_lshlrev_b32_e32 v48, 16, v176
	v_mul_f32_e32 v32, v32, v48
	v_mul_f32_e32 v48, 0xbfb8aa3b, v48
	v_exp_f32_e32 v48, v48
	v_add_co_u32_e32 v98, vcc, s93, v98
	v_lshlrev_b64 v[12:13], 7, v[12:13]
	v_add_f32_e32 v48, 1.0, v48
	v_rcp_f32_e32 v48, v48
	v_addc_co_u32_e32 v99, vcc, 0, v99, vcc
	v_lshl_add_u64 v[12:13], s[34:35], 0, v[12:13]
	v_mul_f32_e32 v32, v32, v48
	v_bfe_u32 v48, v32, 16, 1
	v_add3_u32 v32, v32, v48, s63
	global_store_short_d16_hi v[98:99], v32, off
	v_lshlrev_b32_e32 v32, 16, v175
	v_mul_f32_e32 v16, v16, v32
	v_mul_f32_e32 v32, 0xbfb8aa3b, v32
	v_exp_f32_e32 v32, v32
	v_lshl_add_u64 v[12:13], v[12:13], 0, v[2:3]
	v_lshlrev_b64 v[10:11], 7, v[10:11]
	v_lshl_add_u64 v[10:11], s[34:35], 0, v[10:11]
	v_add_f32_e32 v32, 1.0, v32
	v_rcp_f32_e32 v32, v32
	v_lshl_add_u64 v[10:11], v[10:11], 0, v[2:3]
	v_lshlrev_b64 v[8:9], 7, v[8:9]
	v_lshl_add_u64 v[8:9], s[34:35], 0, v[8:9]
	v_mul_f32_e32 v16, v16, v32
	v_bfe_u32 v32, v16, 16, 1
	v_add3_u32 v16, v16, v32, s63
	global_store_short_d16_hi v[98:99], v16, off offset:64
	s_waitcnt vmcnt(62)
	v_lshlrev_b32_e32 v16, 16, v174
	v_mul_f32_e32 v32, v65, v166
	v_mul_f32_e32 v32, v32, v16
	v_mul_f32_e32 v16, 0xbfb8aa3b, v16
	v_exp_f32_e32 v16, v16
	v_lshlrev_b64 v[64:65], 7, v[96:97]
	v_lshl_add_u64 v[64:65], s[34:35], 0, v[64:65]
	v_lshl_add_u64 v[64:65], v[64:65], 0, v[2:3]
	v_add_f32_e32 v16, 1.0, v16
	v_rcp_f32_e32 v16, v16
	v_lshl_add_u64 v[8:9], v[8:9], 0, v[2:3]
	v_lshlrev_b64 v[6:7], 7, v[6:7]
	v_lshl_add_u64 v[6:7], s[34:35], 0, v[6:7]
	v_mul_f32_e32 v16, v32, v16
	v_bfe_u32 v32, v16, 16, 1
	v_add3_u32 v16, v16, v32, s63
	global_store_short_d16_hi v[64:65], v16, off
	v_lshlrev_b32_e32 v16, 16, v173
	v_mul_f32_e32 v32, v49, v166
	v_mul_f32_e32 v32, v32, v16
	v_mul_f32_e32 v16, 0xbfb8aa3b, v16
	v_exp_f32_e32 v16, v16
	v_lshl_add_u64 v[6:7], v[6:7], 0, v[2:3]
	v_lshlrev_b64 v[4:5], 7, v[4:5]
	v_lshl_add_u64 v[4:5], s[34:35], 0, v[4:5]
	v_add_f32_e32 v16, 1.0, v16
	v_rcp_f32_e32 v16, v16
	v_readlane_b32 s0, v254, 14
	s_add_i32 s76, s76, s66
	s_add_i32 s75, s75, s0
	v_mul_f32_e32 v16, v32, v16
	v_bfe_u32 v32, v16, 16, 1
	v_add3_u32 v16, v16, v32, s63
	global_store_short_d16_hi v[64:65], v16, off offset:64
	s_waitcnt vmcnt(62)
	v_lshlrev_b32_e32 v16, 16, v172
	v_mul_f32_e32 v32, v33, v166
	v_mul_f32_e32 v32, v32, v16
	v_mul_f32_e32 v16, 0xbfb8aa3b, v16
	v_exp_f32_e32 v16, v16
	s_cmpk_gt_i32 s76, 0x3ff
	v_add_f32_e32 v16, 1.0, v16
	v_rcp_f32_e32 v16, v16
	s_nop 0
	v_mul_f32_e32 v16, v32, v16
	v_bfe_u32 v32, v16, 16, 1
	v_add3_u32 v16, v16, v32, s63
	v_add_co_u32_e32 v32, vcc, s93, v64
	s_nop 1
	v_addc_co_u32_e32 v33, vcc, 0, v65, vcc
	global_store_short_d16_hi v[32:33], v16, off
	v_lshlrev_b32_e32 v16, 16, v170
	v_mul_f32_e32 v17, v17, v16
	v_mul_f32_e32 v16, 0xbfb8aa3b, v16
	v_exp_f32_e32 v16, v16
	s_nop 0
	v_add_f32_e32 v16, 1.0, v16
	v_rcp_f32_e32 v16, v16
	s_nop 0
	v_mul_f32_e32 v16, v17, v16
	v_bfe_u32 v17, v16, 16, 1
	v_add3_u32 v16, v16, v17, s63
	global_store_short_d16_hi v[32:33], v16, off offset:64
	s_waitcnt vmcnt(62)
	v_lshlrev_b32_e32 v16, 16, v169
	v_mul_f32_e32 v17, v66, v161
	v_mul_f32_e32 v17, v17, v16
	v_mul_f32_e32 v16, 0xbfb8aa3b, v16
	v_exp_f32_e32 v16, v16
	v_mul_f32_e32 v33, v50, v161
	v_add_f32_e32 v16, 1.0, v16
	v_rcp_f32_e32 v16, v16
	s_nop 0
	v_mul_f32_e32 v16, v17, v16
	v_bfe_u32 v17, v16, 16, 1
	v_add3_u32 v32, v16, v17, s63
	v_lshlrev_b64 v[16:17], 7, v[94:95]
	v_lshl_add_u64 v[16:17], s[34:35], 0, v[16:17]
	v_lshl_add_u64 v[16:17], v[16:17], 0, v[2:3]
	global_store_short_d16_hi v[16:17], v32, off
	v_lshlrev_b32_e32 v32, 16, v168
	v_mul_f32_e32 v33, v33, v32
	v_mul_f32_e32 v32, 0xbfb8aa3b, v32
	v_exp_f32_e32 v32, v32
	s_nop 0
	v_add_f32_e32 v32, 1.0, v32
	v_rcp_f32_e32 v32, v32
	s_nop 0
	v_mul_f32_e32 v32, v33, v32
	v_bfe_u32 v33, v32, 16, 1
	v_add3_u32 v32, v32, v33, s63
	global_store_short_d16_hi v[16:17], v32, off offset:64
	s_waitcnt vmcnt(62)
	v_lshlrev_b32_e32 v32, 16, v167
	v_mul_f32_e32 v33, v34, v161
	v_mul_f32_e32 v33, v33, v32
	v_mul_f32_e32 v32, 0xbfb8aa3b, v32
	v_exp_f32_e32 v32, v32
	v_add_co_u32_e32 v16, vcc, s93, v16
	v_add_f32_e32 v32, 1.0, v32
	v_rcp_f32_e32 v32, v32
	v_addc_co_u32_e32 v17, vcc, 0, v17, vcc
	v_mul_f32_e32 v32, v33, v32
	v_bfe_u32 v33, v32, 16, 1
	v_add3_u32 v32, v32, v33, s63
	global_store_short_d16_hi v[16:17], v32, off
	v_lshlrev_b32_e32 v32, 16, v165
	v_mul_f32_e32 v18, v18, v32
	v_mul_f32_e32 v32, 0xbfb8aa3b, v32
	v_exp_f32_e32 v32, v32
	s_nop 0
	v_add_f32_e32 v32, 1.0, v32
	v_rcp_f32_e32 v32, v32
	s_nop 0
	v_mul_f32_e32 v18, v18, v32
	v_bfe_u32 v32, v18, 16, 1
	v_add3_u32 v18, v18, v32, s63
	global_store_short_d16_hi v[16:17], v18, off offset:64
	s_waitcnt vmcnt(62)
; __device__ __forceinline__ float bf2f(unsigned h) { return __uint_as_float(h << 16); }
; __device__ __forceinline__ unsigned f2bf(float f) { unsigned u = __float_as_uint(f); return (u + 0x7fffu + ((u >> 16) & 1u)) >> 16; }
; __device__ __forceinline__ int crow(int r, int hi) { return (r & 3) + 8 * (r >> 2) + 4 * hi; }
; __device__ __forceinline__ void na_unit3(char* lds, const bf16_t* __restrict__ Qp, const bf16_t* __restrict__ Knp, const bf16_t* __restrict__ Vp, ...
;     ...
; #pragma unroll
;     for (int r = 0; r < 16; ++r) { const long trow = wid * QBLK + crow(r, hi);
; #pragma unroll
;       for (int d0 = 0; d0 < 4; ++d0) { const float z = bf2f(zr[r][d0]); const float v = o[d0][r] * rli[r];
;         const float g = v * z * __builtin_amdgcn_rcpf(1.f + __expf(-z));
;         Op[((size_t)(d0 >> 1) * M_TOK + trow) * 64 + (d0 & 1) * 32 + r32] = (bf16_t)f2bf(g); } } }
	v_lshlrev_b32_e32 v16, 16, v164
	v_mul_f32_e32 v17, v67, v155
	v_mul_f32_e32 v17, v17, v16
	v_mul_f32_e32 v16, 0xbfb8aa3b, v16
	v_exp_f32_e32 v16, v16
	v_mul_f32_e32 v32, v51, v155
	v_add_f32_e32 v16, 1.0, v16
	v_rcp_f32_e32 v16, v16
	s_nop 0
	v_mul_f32_e32 v16, v17, v16
	v_bfe_u32 v17, v16, 16, 1
	v_add3_u32 v18, v16, v17, s63
	v_lshlrev_b64 v[16:17], 7, v[92:93]
	v_lshl_add_u64 v[16:17], s[34:35], 0, v[16:17]
	v_lshl_add_u64 v[16:17], v[16:17], 0, v[2:3]
	global_store_short_d16_hi v[16:17], v18, off
	v_lshlrev_b32_e32 v18, 16, v163
	v_mul_f32_e32 v32, v32, v18
	v_mul_f32_e32 v18, 0xbfb8aa3b, v18
	v_exp_f32_e32 v18, v18
	s_nop 0
	v_add_f32_e32 v18, 1.0, v18
	v_rcp_f32_e32 v18, v18
	s_nop 0
	v_mul_f32_e32 v18, v32, v18
	v_bfe_u32 v32, v18, 16, 1
	v_add3_u32 v18, v18, v32, s63
	global_store_short_d16_hi v[16:17], v18, off offset:64
	s_waitcnt vmcnt(62)
	v_lshlrev_b32_e32 v18, 16, v162
	v_mul_f32_e32 v32, v35, v155
	v_mul_f32_e32 v32, v32, v18
	v_mul_f32_e32 v18, 0xbfb8aa3b, v18
	v_exp_f32_e32 v18, v18
	v_add_co_u32_e32 v16, vcc, s93, v16
	v_add_f32_e32 v18, 1.0, v18
	v_rcp_f32_e32 v18, v18
	v_addc_co_u32_e32 v17, vcc, 0, v17, vcc
	v_mul_f32_e32 v18, v32, v18
	v_bfe_u32 v32, v18, 16, 1
	v_add3_u32 v18, v18, v32, s63
	global_store_short_d16_hi v[16:17], v18, off
	v_lshlrev_b32_e32 v18, 16, v160
	v_mul_f32_e32 v19, v19, v18
	v_mul_f32_e32 v18, 0xbfb8aa3b, v18
	v_exp_f32_e32 v18, v18
	s_nop 0
	v_add_f32_e32 v18, 1.0, v18
	v_rcp_f32_e32 v18, v18
	s_nop 0
	v_mul_f32_e32 v18, v19, v18
	v_bfe_u32 v19, v18, 16, 1
	v_add3_u32 v18, v18, v19, s63
	global_store_short_d16_hi v[16:17], v18, off offset:64
	s_waitcnt vmcnt(62)
	v_lshlrev_b32_e32 v16, 16, v159
	v_mul_f32_e32 v17, v68, v149
	v_mul_f32_e32 v17, v17, v16
	v_mul_f32_e32 v16, 0xbfb8aa3b, v16
	v_exp_f32_e32 v16, v16
	v_mul_f32_e32 v19, v52, v149
	v_add_f32_e32 v16, 1.0, v16
	v_rcp_f32_e32 v16, v16
	s_nop 0
	v_mul_f32_e32 v16, v17, v16
	v_bfe_u32 v17, v16, 16, 1
	v_add3_u32 v18, v16, v17, s63
	v_lshlrev_b64 v[16:17], 7, v[90:91]
	v_lshl_add_u64 v[16:17], s[34:35], 0, v[16:17]
	v_lshl_add_u64 v[16:17], v[16:17], 0, v[2:3]
	global_store_short_d16_hi v[16:17], v18, off
	v_lshlrev_b32_e32 v18, 16, v158
	v_mul_f32_e32 v19, v19, v18
	v_mul_f32_e32 v18, 0xbfb8aa3b, v18
	v_exp_f32_e32 v18, v18
	s_nop 0
	v_add_f32_e32 v18, 1.0, v18
	v_rcp_f32_e32 v18, v18
	s_nop 0
	v_mul_f32_e32 v18, v19, v18
	v_bfe_u32 v19, v18, 16, 1
	v_add3_u32 v18, v18, v19, s63
	global_store_short_d16_hi v[16:17], v18, off offset:64
	s_waitcnt vmcnt(62)
	v_lshlrev_b32_e32 v18, 16, v157
	v_mul_f32_e32 v19, v36, v149
	v_mul_f32_e32 v19, v19, v18
	v_mul_f32_e32 v18, 0xbfb8aa3b, v18
	v_exp_f32_e32 v18, v18
	v_add_co_u32_e32 v16, vcc, s93, v16
	v_add_f32_e32 v18, 1.0, v18
	v_rcp_f32_e32 v18, v18
	v_addc_co_u32_e32 v17, vcc, 0, v17, vcc
	v_mul_f32_e32 v18, v19, v18
	v_bfe_u32 v19, v18, 16, 1
	v_add3_u32 v18, v18, v19, s63
	global_store_short_d16_hi v[16:17], v18, off
	v_lshlrev_b32_e32 v18, 16, v156
	v_mul_f32_e32 v19, v20, v149
	v_mul_f32_e32 v19, v19, v18
	v_mul_f32_e32 v18, 0xbfb8aa3b, v18
	v_exp_f32_e32 v18, v18
	s_nop 0
	v_add_f32_e32 v18, 1.0, v18
	v_rcp_f32_e32 v18, v18
	s_nop 0
	v_mul_f32_e32 v18, v19, v18
	v_bfe_u32 v19, v18, 16, 1
	v_add3_u32 v18, v18, v19, s63
	global_store_short_d16_hi v[16:17], v18, off offset:64
	s_waitcnt vmcnt(62)
	v_lshlrev_b32_e32 v16, 16, v154
	v_mul_f32_e32 v17, v69, v144
	v_mul_f32_e32 v17, v17, v16
	v_mul_f32_e32 v16, 0xbfb8aa3b, v16
	v_exp_f32_e32 v16, v16
	v_mul_f32_e32 v19, v53, v144
	v_add_f32_e32 v16, 1.0, v16
	v_rcp_f32_e32 v16, v16
	s_nop 0
	v_mul_f32_e32 v16, v17, v16
	v_bfe_u32 v17, v16, 16, 1
	v_add3_u32 v18, v16, v17, s63
	v_lshlrev_b64 v[16:17], 7, v[88:89]
	v_lshl_add_u64 v[16:17], s[34:35], 0, v[16:17]
	v_lshl_add_u64 v[16:17], v[16:17], 0, v[2:3]
	global_store_short_d16_hi v[16:17], v18, off
	v_lshlrev_b32_e32 v18, 16, v153
	v_mul_f32_e32 v19, v19, v18
	v_mul_f32_e32 v18, 0xbfb8aa3b, v18
	v_exp_f32_e32 v18, v18
	s_nop 0
	v_add_f32_e32 v18, 1.0, v18
	v_rcp_f32_e32 v18, v18
	s_nop 0
	v_mul_f32_e32 v18, v19, v18
	v_bfe_u32 v19, v18, 16, 1
	v_add3_u32 v18, v18, v19, s63
	global_store_short_d16_hi v[16:17], v18, off offset:64
	s_waitcnt vmcnt(62)
	v_lshlrev_b32_e32 v18, 16, v152
	v_mul_f32_e32 v19, v37, v144
	v_mul_f32_e32 v19, v19, v18
	v_mul_f32_e32 v18, 0xbfb8aa3b, v18
	v_exp_f32_e32 v18, v18
	v_add_co_u32_e32 v16, vcc, s93, v16
	v_add_f32_e32 v18, 1.0, v18
	v_rcp_f32_e32 v18, v18
	v_addc_co_u32_e32 v17, vcc, 0, v17, vcc
	v_mul_f32_e32 v18, v19, v18
	v_bfe_u32 v19, v18, 16, 1
	v_add3_u32 v18, v18, v19, s63
	global_store_short_d16_hi v[16:17], v18, off
	v_lshlrev_b32_e32 v18, 16, v151
	v_mul_f32_e32 v19, v21, v144
	v_mul_f32_e32 v19, v19, v18
	v_mul_f32_e32 v18, 0xbfb8aa3b, v18
	v_exp_f32_e32 v18, v18
	s_nop 0
	v_add_f32_e32 v18, 1.0, v18
	v_rcp_f32_e32 v18, v18
	s_nop 0
	v_mul_f32_e32 v18, v19, v18
	v_bfe_u32 v19, v18, 16, 1
	v_add3_u32 v18, v18, v19, s63
	global_store_short_d16_hi v[16:17], v18, off offset:64
	s_waitcnt vmcnt(62)
	v_lshlrev_b32_e32 v16, 16, v150
	v_mul_f32_e32 v17, v70, v139
	v_mul_f32_e32 v17, v17, v16
	v_mul_f32_e32 v16, 0xbfb8aa3b, v16
	v_exp_f32_e32 v16, v16
	v_mul_f32_e32 v19, v54, v139
	v_add_f32_e32 v16, 1.0, v16
	v_rcp_f32_e32 v16, v16
	s_nop 0
	v_mul_f32_e32 v16, v17, v16
	v_bfe_u32 v17, v16, 16, 1
	v_add3_u32 v18, v16, v17, s63
	v_lshlrev_b64 v[16:17], 7, v[86:87]
	v_lshl_add_u64 v[16:17], s[34:35], 0, v[16:17]
	v_lshl_add_u64 v[16:17], v[16:17], 0, v[2:3]
	global_store_short_d16_hi v[16:17], v18, off
	v_lshlrev_b32_e32 v18, 16, v148
	v_mul_f32_e32 v19, v19, v18
	v_mul_f32_e32 v18, 0xbfb8aa3b, v18
	v_exp_f32_e32 v18, v18
	s_nop 0
	v_add_f32_e32 v18, 1.0, v18
	v_rcp_f32_e32 v18, v18
	s_nop 0
	v_mul_f32_e32 v18, v19, v18
	v_bfe_u32 v19, v18, 16, 1
	v_add3_u32 v18, v18, v19, s63
	global_store_short_d16_hi v[16:17], v18, off offset:64
	s_waitcnt vmcnt(62)
; __device__ __forceinline__ float bf2f(unsigned h) { return __uint_as_float(h << 16); }
; __device__ __forceinline__ unsigned f2bf(float f) { unsigned u = __float_as_uint(f); return (u + 0x7fffu + ((u >> 16) & 1u)) >> 16; }
; __device__ __forceinline__ int crow(int r, int hi) { return (r & 3) + 8 * (r >> 2) + 4 * hi; }
; __device__ __forceinline__ void na_unit3(char* lds, const bf16_t* __restrict__ Qp, const bf16_t* __restrict__ Knp, const bf16_t* __restrict__ Vp, ...
;     ...
; #pragma unroll
;     for (int r = 0; r < 16; ++r) { const long trow = wid * QBLK + crow(r, hi);
; #pragma unroll
;       for (int d0 = 0; d0 < 4; ++d0) { const float z = bf2f(zr[r][d0]); const float v = o[d0][r] * rli[r];
;         const float g = v * z * __builtin_amdgcn_rcpf(1.f + __expf(-z));
;         Op[((size_t)(d0 >> 1) * M_TOK + trow) * 64 + (d0 & 1) * 32 + r32] = (bf16_t)f2bf(g); } } }
	v_lshlrev_b32_e32 v18, 16, v147
	v_mul_f32_e32 v19, v38, v139
	v_mul_f32_e32 v19, v19, v18
	v_mul_f32_e32 v18, 0xbfb8aa3b, v18
	v_exp_f32_e32 v18, v18
	v_add_co_u32_e32 v16, vcc, s93, v16
	v_add_f32_e32 v18, 1.0, v18
	v_rcp_f32_e32 v18, v18
	v_addc_co_u32_e32 v17, vcc, 0, v17, vcc
	v_mul_f32_e32 v18, v19, v18
	v_bfe_u32 v19, v18, 16, 1
	v_add3_u32 v18, v18, v19, s63
	global_store_short_d16_hi v[16:17], v18, off
	v_lshlrev_b32_e32 v18, 16, v146
	v_mul_f32_e32 v19, v22, v139
	v_mul_f32_e32 v19, v19, v18
	v_mul_f32_e32 v18, 0xbfb8aa3b, v18
	v_exp_f32_e32 v18, v18
	s_nop 0
	v_add_f32_e32 v18, 1.0, v18
	v_rcp_f32_e32 v18, v18
	s_nop 0
	v_mul_f32_e32 v18, v19, v18
	v_bfe_u32 v19, v18, 16, 1
	v_add3_u32 v18, v18, v19, s63
	global_store_short_d16_hi v[16:17], v18, off offset:64
	s_waitcnt vmcnt(62)
	v_lshlrev_b32_e32 v16, 16, v145
	v_mul_f32_e32 v17, v71, v133
	v_mul_f32_e32 v17, v17, v16
	v_mul_f32_e32 v16, 0xbfb8aa3b, v16
	v_exp_f32_e32 v16, v16
	v_mul_f32_e32 v19, v55, v133
	v_add_f32_e32 v16, 1.0, v16
	v_rcp_f32_e32 v16, v16
	s_nop 0
	v_mul_f32_e32 v16, v17, v16
	v_bfe_u32 v17, v16, 16, 1
	v_add3_u32 v18, v16, v17, s63
	v_lshlrev_b64 v[16:17], 7, v[84:85]
	v_lshl_add_u64 v[16:17], s[34:35], 0, v[16:17]
	v_lshl_add_u64 v[16:17], v[16:17], 0, v[2:3]
	global_store_short_d16_hi v[16:17], v18, off
	v_lshlrev_b32_e32 v18, 16, v143
	v_mul_f32_e32 v19, v19, v18
	v_mul_f32_e32 v18, 0xbfb8aa3b, v18
	v_exp_f32_e32 v18, v18
	s_nop 0
	v_add_f32_e32 v18, 1.0, v18
	v_rcp_f32_e32 v18, v18
	s_nop 0
	v_mul_f32_e32 v18, v19, v18
	v_bfe_u32 v19, v18, 16, 1
	v_add3_u32 v18, v18, v19, s63
	global_store_short_d16_hi v[16:17], v18, off offset:64
	s_waitcnt vmcnt(62)
	v_lshlrev_b32_e32 v18, 16, v142
	v_mul_f32_e32 v19, v39, v133
	v_mul_f32_e32 v19, v19, v18
	v_mul_f32_e32 v18, 0xbfb8aa3b, v18
	v_exp_f32_e32 v18, v18
	v_add_co_u32_e32 v16, vcc, s93, v16
	v_add_f32_e32 v18, 1.0, v18
	v_rcp_f32_e32 v18, v18
	v_addc_co_u32_e32 v17, vcc, 0, v17, vcc
	v_mul_f32_e32 v18, v19, v18
	v_bfe_u32 v19, v18, 16, 1
	v_add3_u32 v18, v18, v19, s63
	global_store_short_d16_hi v[16:17], v18, off
	v_lshlrev_b32_e32 v18, 16, v141
	v_mul_f32_e32 v19, v23, v133
	v_mul_f32_e32 v19, v19, v18
	v_mul_f32_e32 v18, 0xbfb8aa3b, v18
	v_exp_f32_e32 v18, v18
	s_nop 0
	v_add_f32_e32 v18, 1.0, v18
	v_rcp_f32_e32 v18, v18
	s_nop 0
	v_mul_f32_e32 v18, v19, v18
	v_bfe_u32 v19, v18, 16, 1
	v_add3_u32 v18, v18, v19, s63
	global_store_short_d16_hi v[16:17], v18, off offset:64
	s_waitcnt vmcnt(62)
	v_lshlrev_b32_e32 v16, 16, v140
	v_mul_f32_e32 v17, v72, v128
	v_mul_f32_e32 v17, v17, v16
	v_mul_f32_e32 v16, 0xbfb8aa3b, v16
	v_exp_f32_e32 v16, v16
	v_mul_f32_e32 v19, v56, v128
	v_add_f32_e32 v16, 1.0, v16
	v_rcp_f32_e32 v16, v16
	s_nop 0
	v_mul_f32_e32 v16, v17, v16
	v_bfe_u32 v17, v16, 16, 1
	v_add3_u32 v18, v16, v17, s63
	v_lshlrev_b64 v[16:17], 7, v[82:83]
	v_lshl_add_u64 v[16:17], s[34:35], 0, v[16:17]
	v_lshl_add_u64 v[16:17], v[16:17], 0, v[2:3]
	global_store_short_d16_hi v[16:17], v18, off
	v_lshlrev_b32_e32 v18, 16, v138
	v_mul_f32_e32 v19, v19, v18
	v_mul_f32_e32 v18, 0xbfb8aa3b, v18
	v_exp_f32_e32 v18, v18
	s_nop 0
	v_add_f32_e32 v18, 1.0, v18
	v_rcp_f32_e32 v18, v18
	s_nop 0
	v_mul_f32_e32 v18, v19, v18
	v_bfe_u32 v19, v18, 16, 1
	v_add3_u32 v18, v18, v19, s63
	global_store_short_d16_hi v[16:17], v18, off offset:64
	s_waitcnt vmcnt(62)
	v_lshlrev_b32_e32 v18, 16, v137
	v_mul_f32_e32 v19, v40, v128
	v_mul_f32_e32 v19, v19, v18
	v_mul_f32_e32 v18, 0xbfb8aa3b, v18
	v_exp_f32_e32 v18, v18
	v_add_co_u32_e32 v16, vcc, s93, v16
	v_add_f32_e32 v18, 1.0, v18
	v_rcp_f32_e32 v18, v18
	v_addc_co_u32_e32 v17, vcc, 0, v17, vcc
	v_mul_f32_e32 v18, v19, v18
	v_bfe_u32 v19, v18, 16, 1
	v_add3_u32 v18, v18, v19, s63
	global_store_short_d16_hi v[16:17], v18, off
	v_lshlrev_b32_e32 v18, 16, v136
	v_mul_f32_e32 v19, v24, v128
	v_mul_f32_e32 v19, v19, v18
	v_mul_f32_e32 v18, 0xbfb8aa3b, v18
	v_exp_f32_e32 v18, v18
	s_nop 0
	v_add_f32_e32 v18, 1.0, v18
	v_rcp_f32_e32 v18, v18
	s_nop 0
	v_mul_f32_e32 v18, v19, v18
	v_bfe_u32 v19, v18, 16, 1
	v_add3_u32 v18, v18, v19, s63
	global_store_short_d16_hi v[16:17], v18, off offset:64
	s_waitcnt vmcnt(62)
	v_lshlrev_b32_e32 v16, 16, v135
	v_mul_f32_e32 v17, v73, v122
	v_mul_f32_e32 v17, v17, v16
	v_mul_f32_e32 v16, 0xbfb8aa3b, v16
	v_exp_f32_e32 v16, v16
	v_mul_f32_e32 v19, v57, v122
	v_add_f32_e32 v16, 1.0, v16
	v_rcp_f32_e32 v16, v16
	s_nop 0
	v_mul_f32_e32 v16, v17, v16
	v_bfe_u32 v17, v16, 16, 1
	v_add3_u32 v18, v16, v17, s63
	v_lshlrev_b64 v[16:17], 7, v[80:81]
	v_lshl_add_u64 v[16:17], s[34:35], 0, v[16:17]
	v_lshl_add_u64 v[16:17], v[16:17], 0, v[2:3]
	global_store_short_d16_hi v[16:17], v18, off
	v_lshlrev_b32_e32 v18, 16, v134
	v_mul_f32_e32 v19, v19, v18
	v_mul_f32_e32 v18, 0xbfb8aa3b, v18
	v_exp_f32_e32 v18, v18
	v_lshl_add_u64 v[2:3], v[4:5], 0, v[2:3]
	s_waitcnt vmcnt(39)
	v_lshlrev_b32_e32 v4, 16, v104
	v_mul_f32_e32 v5, v63, v1
	v_add_f32_e32 v18, 1.0, v18
	v_rcp_f32_e32 v18, v18
	v_mul_f32_e32 v5, v5, v4
	v_mul_f32_e32 v4, 0xbfb8aa3b, v4
	v_exp_f32_e32 v4, v4
	v_mul_f32_e32 v18, v19, v18
	v_bfe_u32 v19, v18, 16, 1
	v_add3_u32 v18, v18, v19, s63
	global_store_short_d16_hi v[16:17], v18, off offset:64
	v_lshlrev_b32_e32 v18, 16, v132
	v_mul_f32_e32 v19, v41, v122
	v_mul_f32_e32 v19, v19, v18
	v_mul_f32_e32 v18, 0xbfb8aa3b, v18
	v_exp_f32_e32 v18, v18
	v_add_co_u32_e32 v16, vcc, s93, v16
	v_add_f32_e32 v4, 1.0, v4
	v_add_f32_e32 v18, 1.0, v18
	v_rcp_f32_e32 v18, v18
	v_addc_co_u32_e32 v17, vcc, 0, v17, vcc
	v_rcp_f32_e32 v4, v4
	v_mul_f32_e32 v18, v19, v18
	v_bfe_u32 v19, v18, 16, 1
	v_add3_u32 v18, v18, v19, s63
	global_store_short_d16_hi v[16:17], v18, off
	v_lshlrev_b32_e32 v18, 16, v131
	v_mul_f32_e32 v19, v25, v122
	v_mul_f32_e32 v19, v19, v18
	v_mul_f32_e32 v18, 0xbfb8aa3b, v18
	v_exp_f32_e32 v18, v18
	v_mul_f32_e32 v4, v5, v4
	v_bfe_u32 v5, v4, 16, 1
	v_add3_u32 v4, v4, v5, s63
	v_add_f32_e32 v18, 1.0, v18
	v_rcp_f32_e32 v18, v18
	global_store_short_d16_hi v[2:3], v4, off offset:64
	s_waitcnt vmcnt(41)
; __device__ __forceinline__ float bf2f(unsigned h) { return __uint_as_float(h << 16); }
; __device__ __forceinline__ unsigned f2bf(float f) { unsigned u = __float_as_uint(f); return (u + 0x7fffu + ((u >> 16) & 1u)) >> 16; }
; __device__ __forceinline__ int crow(int r, int hi) { return (r & 3) + 8 * (r >> 2) + 4 * hi; }
; __device__ __forceinline__ void na_unit3(char* lds, const bf16_t* __restrict__ Qp, const bf16_t* __restrict__ Knp, const bf16_t* __restrict__ Vp, ...
;     ...
; #pragma unroll
;     for (int r = 0; r < 16; ++r) { const long trow = wid * QBLK + crow(r, hi);
; #pragma unroll
;       for (int d0 = 0; d0 < 4; ++d0) { const float z = bf2f(zr[r][d0]); const float v = o[d0][r] * rli[r];
;         const float g = v * z * __builtin_amdgcn_rcpf(1.f + __expf(-z));
;         Op[((size_t)(d0 >> 1) * M_TOK + trow) * 64 + (d0 & 1) * 32 + r32] = (bf16_t)f2bf(g); } } }
	v_lshlrev_b32_e32 v4, 16, v101
	v_mul_f32_e32 v5, v47, v1
	v_mul_f32_e32 v18, v19, v18
	v_bfe_u32 v19, v18, 16, 1
	v_add3_u32 v18, v18, v19, s63
	global_store_short_d16_hi v[16:17], v18, off offset:64
	v_lshlrev_b32_e32 v16, 16, v130
	v_mul_f32_e32 v17, v74, v117
	v_mul_f32_e32 v17, v17, v16
	v_mul_f32_e32 v16, 0xbfb8aa3b, v16
	v_exp_f32_e32 v16, v16
	v_mul_f32_e32 v5, v5, v4
	v_mul_f32_e32 v4, 0xbfb8aa3b, v4
	v_exp_f32_e32 v4, v4
	v_add_f32_e32 v16, 1.0, v16
	v_rcp_f32_e32 v16, v16
	v_add_f32_e32 v4, 1.0, v4
	v_rcp_f32_e32 v4, v4
	v_mul_f32_e32 v16, v17, v16
	v_bfe_u32 v17, v16, 16, 1
	v_add3_u32 v16, v16, v17, s63
	global_store_short_d16_hi v[14:15], v16, off
	v_lshlrev_b32_e32 v16, 16, v129
	v_mul_f32_e32 v17, v58, v117
	v_mul_f32_e32 v17, v17, v16
	v_mul_f32_e32 v16, 0xbfb8aa3b, v16
	v_exp_f32_e32 v16, v16
	v_mul_f32_e32 v4, v5, v4
	v_bfe_u32 v5, v4, 16, 1
	v_add3_u32 v4, v4, v5, s63
	v_add_f32_e32 v16, 1.0, v16
	v_rcp_f32_e32 v16, v16
	s_nop 0
	v_mul_f32_e32 v16, v17, v16
	v_bfe_u32 v17, v16, 16, 1
	v_add3_u32 v16, v16, v17, s63
	global_store_short_d16_hi v[14:15], v16, off offset:64
	v_lshlrev_b32_e32 v16, 16, v127
	v_mul_f32_e32 v17, v42, v117
	v_mul_f32_e32 v17, v17, v16
	v_mul_f32_e32 v16, 0xbfb8aa3b, v16
	v_exp_f32_e32 v16, v16
	v_add_co_u32_e32 v14, vcc, s93, v14
	v_add_f32_e32 v16, 1.0, v16
	v_rcp_f32_e32 v16, v16
	v_addc_co_u32_e32 v15, vcc, 0, v15, vcc
	v_mul_f32_e32 v16, v17, v16
	v_bfe_u32 v17, v16, 16, 1
	v_add3_u32 v16, v16, v17, s63
	global_store_short_d16_hi v[14:15], v16, off
	v_lshlrev_b32_e32 v16, 16, v126
	v_mul_f32_e32 v17, v26, v117
	v_mul_f32_e32 v17, v17, v16
	v_mul_f32_e32 v16, 0xbfb8aa3b, v16
	v_exp_f32_e32 v16, v16
	s_nop 0
	v_add_f32_e32 v16, 1.0, v16
	v_rcp_f32_e32 v16, v16
	s_nop 0
	v_mul_f32_e32 v16, v17, v16
	v_bfe_u32 v17, v16, 16, 1
	v_add3_u32 v16, v16, v17, s63
	global_store_short_d16_hi v[14:15], v16, off offset:64
	v_lshlrev_b32_e32 v14, 16, v125
	v_mul_f32_e32 v15, v75, v111
	v_mul_f32_e32 v15, v15, v14
	v_mul_f32_e32 v14, 0xbfb8aa3b, v14
	v_exp_f32_e32 v14, v14
	s_nop 0
	v_add_f32_e32 v14, 1.0, v14
	v_rcp_f32_e32 v14, v14
	s_nop 0
	v_mul_f32_e32 v14, v15, v14
	v_bfe_u32 v15, v14, 16, 1
	v_add3_u32 v14, v14, v15, s63
	global_store_short_d16_hi v[12:13], v14, off
	v_lshlrev_b32_e32 v14, 16, v124
	v_mul_f32_e32 v15, v59, v111
	v_mul_f32_e32 v15, v15, v14
	v_mul_f32_e32 v14, 0xbfb8aa3b, v14
	v_exp_f32_e32 v14, v14
	s_nop 0
	v_add_f32_e32 v14, 1.0, v14
	v_rcp_f32_e32 v14, v14
	s_nop 0
	v_mul_f32_e32 v14, v15, v14
	v_bfe_u32 v15, v14, 16, 1
	v_add3_u32 v14, v14, v15, s63
	global_store_short_d16_hi v[12:13], v14, off offset:64
	v_lshlrev_b32_e32 v14, 16, v123
	v_mul_f32_e32 v15, v43, v111
	v_mul_f32_e32 v15, v15, v14
	v_mul_f32_e32 v14, 0xbfb8aa3b, v14
	v_exp_f32_e32 v14, v14
	v_add_co_u32_e32 v12, vcc, s93, v12
	v_add_f32_e32 v14, 1.0, v14
	v_rcp_f32_e32 v14, v14
	v_addc_co_u32_e32 v13, vcc, 0, v13, vcc
	v_mul_f32_e32 v14, v15, v14
	v_bfe_u32 v15, v14, 16, 1
	v_add3_u32 v14, v14, v15, s63
	global_store_short_d16_hi v[12:13], v14, off
	v_lshlrev_b32_e32 v14, 16, v121
	v_mul_f32_e32 v15, v27, v111
	v_mul_f32_e32 v15, v15, v14
	v_mul_f32_e32 v14, 0xbfb8aa3b, v14
	v_exp_f32_e32 v14, v14
	s_nop 0
	v_add_f32_e32 v14, 1.0, v14
	v_rcp_f32_e32 v14, v14
	s_nop 0
	v_mul_f32_e32 v14, v15, v14
	v_bfe_u32 v15, v14, 16, 1
	v_add3_u32 v14, v14, v15, s63
	global_store_short_d16_hi v[12:13], v14, off offset:64
	v_lshlrev_b32_e32 v12, 16, v120
	v_mul_f32_e32 v13, v76, v105
	v_mul_f32_e32 v13, v13, v12
	v_mul_f32_e32 v12, 0xbfb8aa3b, v12
	v_exp_f32_e32 v12, v12
	s_nop 0
	v_add_f32_e32 v12, 1.0, v12
	v_rcp_f32_e32 v12, v12
	s_nop 0
	v_mul_f32_e32 v12, v13, v12
	v_bfe_u32 v13, v12, 16, 1
	v_add3_u32 v12, v12, v13, s63
	global_store_short_d16_hi v[10:11], v12, off
	v_lshlrev_b32_e32 v12, 16, v119
	v_mul_f32_e32 v13, v60, v105
	v_mul_f32_e32 v13, v13, v12
	v_mul_f32_e32 v12, 0xbfb8aa3b, v12
	v_exp_f32_e32 v12, v12
	s_nop 0
	v_add_f32_e32 v12, 1.0, v12
	v_rcp_f32_e32 v12, v12
	s_nop 0
	v_mul_f32_e32 v12, v13, v12
	v_bfe_u32 v13, v12, 16, 1
	v_add3_u32 v12, v12, v13, s63
	global_store_short_d16_hi v[10:11], v12, off offset:64
	v_lshlrev_b32_e32 v12, 16, v118
	v_mul_f32_e32 v13, v44, v105
	v_mul_f32_e32 v13, v13, v12
	v_mul_f32_e32 v12, 0xbfb8aa3b, v12
	v_exp_f32_e32 v12, v12
	v_add_co_u32_e32 v10, vcc, s93, v10
	v_add_f32_e32 v12, 1.0, v12
; __device__ __forceinline__ float bf2f(unsigned h) { return __uint_as_float(h << 16); }
; __device__ __forceinline__ unsigned f2bf(float f) { unsigned u = __float_as_uint(f); return (u + 0x7fffu + ((u >> 16) & 1u)) >> 16; }
; __device__ __forceinline__ int crow(int r, int hi) { return (r & 3) + 8 * (r >> 2) + 4 * hi; }
; __device__ __forceinline__ void na_unit3(char* lds, const bf16_t* __restrict__ Qp, const bf16_t* __restrict__ Knp, const bf16_t* __restrict__ Vp, ...
;     ...
; #pragma unroll
;     for (int r = 0; r < 16; ++r) { const long trow = wid * QBLK + crow(r, hi);
; #pragma unroll
;       for (int d0 = 0; d0 < 4; ++d0) { const float z = bf2f(zr[r][d0]); const float v = o[d0][r] * rli[r];
;         const float g = v * z * __builtin_amdgcn_rcpf(1.f + __expf(-z));
;         Op[((size_t)(d0 >> 1) * M_TOK + trow) * 64 + (d0 & 1) * 32 + r32] = (bf16_t)f2bf(g); } } }
;   asm volatile("s_waitcnt vmcnt(0) lgkmcnt(0)\n\ts_barrier" ::: "memory");
	v_rcp_f32_e32 v12, v12
	v_addc_co_u32_e32 v11, vcc, 0, v11, vcc
	v_mul_f32_e32 v12, v13, v12
	v_bfe_u32 v13, v12, 16, 1
	v_add3_u32 v12, v12, v13, s63
	global_store_short_d16_hi v[10:11], v12, off
	v_lshlrev_b32_e32 v12, 16, v116
	v_mul_f32_e32 v13, v28, v105
	v_mul_f32_e32 v13, v13, v12
	v_mul_f32_e32 v12, 0xbfb8aa3b, v12
	v_exp_f32_e32 v12, v12
	s_nop 0
	v_add_f32_e32 v12, 1.0, v12
	v_rcp_f32_e32 v12, v12
	s_nop 0
	v_mul_f32_e32 v12, v13, v12
	v_bfe_u32 v13, v12, 16, 1
	v_add3_u32 v12, v12, v13, s63
	global_store_short_d16_hi v[10:11], v12, off offset:64
	v_lshlrev_b32_e32 v10, 16, v115
	v_mul_f32_e32 v11, v77, v103
	v_mul_f32_e32 v11, v11, v10
	v_mul_f32_e32 v10, 0xbfb8aa3b, v10
	v_exp_f32_e32 v10, v10
	s_nop 0
	v_add_f32_e32 v10, 1.0, v10
	v_rcp_f32_e32 v10, v10
	s_nop 0
	v_mul_f32_e32 v10, v11, v10
	v_bfe_u32 v11, v10, 16, 1
	v_add3_u32 v10, v10, v11, s63
	global_store_short_d16_hi v[8:9], v10, off
	v_lshlrev_b32_e32 v10, 16, v114
	v_mul_f32_e32 v11, v61, v103
	v_mul_f32_e32 v11, v11, v10
	v_mul_f32_e32 v10, 0xbfb8aa3b, v10
	v_exp_f32_e32 v10, v10
	s_nop 0
	v_add_f32_e32 v10, 1.0, v10
	v_rcp_f32_e32 v10, v10
	s_nop 0
	v_mul_f32_e32 v10, v11, v10
	v_bfe_u32 v11, v10, 16, 1
	v_add3_u32 v10, v10, v11, s63
	global_store_short_d16_hi v[8:9], v10, off offset:64
	v_lshlrev_b32_e32 v10, 16, v113
	v_mul_f32_e32 v11, v45, v103
	v_mul_f32_e32 v11, v11, v10
	v_mul_f32_e32 v10, 0xbfb8aa3b, v10
	v_exp_f32_e32 v10, v10
	v_add_co_u32_e32 v8, vcc, s93, v8
	v_add_f32_e32 v10, 1.0, v10
	v_rcp_f32_e32 v10, v10
	v_addc_co_u32_e32 v9, vcc, 0, v9, vcc
	v_mul_f32_e32 v10, v11, v10
	v_bfe_u32 v11, v10, 16, 1
	v_add3_u32 v10, v10, v11, s63
	global_store_short_d16_hi v[8:9], v10, off
	v_lshlrev_b32_e32 v10, 16, v112
	v_mul_f32_e32 v11, v29, v103
	v_mul_f32_e32 v11, v11, v10
	v_mul_f32_e32 v10, 0xbfb8aa3b, v10
	v_exp_f32_e32 v10, v10
	s_nop 0
	v_add_f32_e32 v10, 1.0, v10
	v_rcp_f32_e32 v10, v10
	s_nop 0
	v_mul_f32_e32 v10, v11, v10
	v_bfe_u32 v11, v10, 16, 1
	v_add3_u32 v10, v10, v11, s63
	global_store_short_d16_hi v[8:9], v10, off offset:64
	v_lshlrev_b32_e32 v8, 16, v110
	v_mul_f32_e32 v9, v78, v102
	v_mul_f32_e32 v9, v9, v8
	v_mul_f32_e32 v8, 0xbfb8aa3b, v8
	v_exp_f32_e32 v8, v8
	s_nop 0
	v_add_f32_e32 v8, 1.0, v8
	v_rcp_f32_e32 v8, v8
	s_nop 0
	v_mul_f32_e32 v8, v9, v8
	v_bfe_u32 v9, v8, 16, 1
	v_add3_u32 v8, v8, v9, s63
	global_store_short_d16_hi v[6:7], v8, off
	v_lshlrev_b32_e32 v8, 16, v109
	v_mul_f32_e32 v9, v62, v102
	v_mul_f32_e32 v9, v9, v8
	v_mul_f32_e32 v8, 0xbfb8aa3b, v8
	v_exp_f32_e32 v8, v8
	s_nop 0
	v_add_f32_e32 v8, 1.0, v8
	v_rcp_f32_e32 v8, v8
	s_nop 0
	v_mul_f32_e32 v8, v9, v8
	v_bfe_u32 v9, v8, 16, 1
	v_add3_u32 v8, v8, v9, s63
	global_store_short_d16_hi v[6:7], v8, off offset:64
	v_lshlrev_b32_e32 v8, 16, v108
	v_mul_f32_e32 v9, v46, v102
	v_mul_f32_e32 v9, v9, v8
	v_mul_f32_e32 v8, 0xbfb8aa3b, v8
	v_exp_f32_e32 v8, v8
	v_add_co_u32_e32 v6, vcc, s93, v6
	v_add_f32_e32 v8, 1.0, v8
	v_rcp_f32_e32 v8, v8
	v_addc_co_u32_e32 v7, vcc, 0, v7, vcc
	v_mul_f32_e32 v8, v9, v8
	v_bfe_u32 v9, v8, 16, 1
	v_add3_u32 v8, v8, v9, s63
	global_store_short_d16_hi v[6:7], v8, off
	v_lshlrev_b32_e32 v8, 16, v107
	v_mul_f32_e32 v9, v30, v102
	v_mul_f32_e32 v9, v9, v8
	v_mul_f32_e32 v8, 0xbfb8aa3b, v8
	v_exp_f32_e32 v8, v8
	s_nop 0
	v_add_f32_e32 v8, 1.0, v8
	v_rcp_f32_e32 v8, v8
	s_nop 0
	v_mul_f32_e32 v8, v9, v8
	v_bfe_u32 v9, v8, 16, 1
	v_add3_u32 v8, v8, v9, s63
	global_store_short_d16_hi v[6:7], v8, off offset:64
	v_lshlrev_b32_e32 v6, 16, v106
	v_mul_f32_e32 v7, v79, v1
	v_mul_f32_e32 v7, v7, v6
	v_mul_f32_e32 v6, 0xbfb8aa3b, v6
	v_exp_f32_e32 v6, v6
	v_mul_f32_e32 v1, v31, v1
	v_add_f32_e32 v6, 1.0, v6
	v_rcp_f32_e32 v6, v6
	s_nop 0
	v_mul_f32_e32 v6, v7, v6
	v_bfe_u32 v7, v6, 16, 1
	v_add3_u32 v6, v6, v7, s63
	global_store_short_d16_hi v[2:3], v6, off
	v_add_co_u32_e32 v2, vcc, s93, v2
	s_nop 1
	v_addc_co_u32_e32 v3, vcc, 0, v3, vcc
	global_store_short_d16_hi v[2:3], v4, off
	s_waitcnt vmcnt(62)
	v_lshlrev_b32_e32 v4, 16, v100
	v_mul_f32_e32 v1, v1, v4
	v_mul_f32_e32 v4, 0xbfb8aa3b, v4
	v_exp_f32_e32 v4, v4
	s_nop 0
	v_add_f32_e32 v4, 1.0, v4
	v_rcp_f32_e32 v4, v4
	s_nop 0
	v_mul_f32_e32 v1, v1, v4
	v_bfe_u32 v4, v1, 16, 1
	v_add3_u32 v1, v1, v4, s63
	global_store_short_d16_hi v[2:3], v1, off offset:64
	s_waitcnt vmcnt(0) lgkmcnt(0)
	s_barrier
	s_cbranch_scc1 .LBB0_352
